# added: combine gather waits removed, DPP wave reductions, gather-index loads hoisted, batched LDS reads in GLA output section
# speedup vs baseline: 1.0573x; 1.0079x over previous
; __device__ void phase_combine(const Params& p, int l, float* outp) {
;     ...
;         unsigned long long em = __ballot(myslot >= 0) & 0xffffull;
;         while (em) {
;             int sl[4];
; #pragma unroll
;             for (int k = 0; k < 4; ++k) { sl[k] = -1; if (em) { const int e = __builtin_ctzll(em); em &= em - 1; sl[k] = __builtin_amdgcn_readlane(myslot, e); } }
;             u32x2 yw[4][4];
; #pragma unroll
;             for (int k = 0; k < 4; ++k) if (sl[k] >= 0) {
; #pragma unroll
;                 for (int j = 0; j < 4; ++j) yw[k][j] = *(const u32x2*)(YB + (size_t)sl[k] * DM + lane * 4 + 256 * j); }
.LBB0_55:
	s_lshl_b64 s[18:19], s[90:91], 11
	v_lshl_add_u64 v[106:107], v[66:67], 0, s[18:19]
	global_load_dwordx2 v[82:83], v[106:107], off
	global_load_dwordx2 v[90:91], v[106:107], off offset:512
	global_load_dwordx2 v[98:99], v[106:107], off offset:1024
	s_nop 0
	global_load_dwordx2 v[106:107], v[106:107], off offset:1536
.LBB0_56:
	s_cmp_gt_i32 s16, -1
	s_cselect_b64 s[18:19], -1, 0
	s_cmp_lt_i32 s16, 0
	s_cbranch_scc1 .LBB0_58
	s_mov_b32 s17, s91
	s_lshl_b64 s[16:17], s[16:17], 11
	v_lshl_add_u64 v[108:109], v[66:67], 0, s[16:17]
	global_load_dwordx2 v[84:85], v[108:109], off
	global_load_dwordx2 v[92:93], v[108:109], off offset:512
	global_load_dwordx2 v[100:101], v[108:109], off offset:1024
	s_nop 0
	global_load_dwordx2 v[108:109], v[108:109], off offset:1536
.LBB0_58:
	s_cmp_gt_i32 s14, -1
	s_cselect_b64 s[16:17], -1, 0
	s_cmp_lt_i32 s14, 0
	s_cbranch_scc1 .LBB0_60
	s_mov_b32 s15, s91
	s_lshl_b64 s[14:15], s[14:15], 11
	v_lshl_add_u64 v[110:111], v[66:67], 0, s[14:15]
	global_load_dwordx2 v[86:87], v[110:111], off
	global_load_dwordx2 v[94:95], v[110:111], off offset:512
	global_load_dwordx2 v[102:103], v[110:111], off offset:1024
	s_nop 0
	global_load_dwordx2 v[110:111], v[110:111], off offset:1536
.LBB0_60:
	s_cmp_gt_i32 s22, -1
	s_cselect_b64 s[14:15], -1, 0
	s_cmp_lt_i32 s22, 0
	s_cbranch_scc1 .LBB0_62
	s_mov_b32 s23, s91
	s_lshl_b64 s[22:23], s[22:23], 11
	v_lshl_add_u64 v[112:113], v[66:67], 0, s[22:23]
	global_load_dwordx2 v[88:89], v[112:113], off
	global_load_dwordx2 v[96:97], v[112:113], off offset:512
	global_load_dwordx2 v[104:105], v[112:113], off offset:1024
	s_nop 0
	global_load_dwordx2 v[112:113], v[112:113], off offset:1536

; __device__ __forceinline__ unsigned cvt_pk_bf16(float lo, float hi) { unsigned r; asm("v_cvt_pk_bf16_f32 %0, %1, %2" : "=v"(r) : "v"(lo), "v"(hi)); return r; }
; __device__ __forceinline__ float wave_sum(float v) {
; #pragma unroll
;     for (int o = 32; o >= 1; o >>= 1) v += __shfl_xor(v, o);
;     return v;
; __device__ void phase_combine(const Params& p, int l, float* outp) {
;     ...
;         float s = 0.f;
; #pragma unroll
;         for (int j = 0; j < 4; ++j) s += (v[j][0] + v[j][1]) + (v[j][2] + v[j][3]);
;         const float mean = wave_sum(s) * (1.0f / 1024.0f); float q = 0.f;
; #pragma unroll
;         for (int j = 0; j < 4; ++j) { v[j] = v[j] - mean; q += (v[j][0] * v[j][0] + v[j][1] * v[j][1]) + (v[j][2] * v[j][2] + v[j][3] * v[j][3]); }
;         const float rstd = rsqrtf(wave_sum(q) * (1.0f / 1024.0f) + 1e-5f);
; #pragma unroll
;         for (int j = 0; j < 4; ++j) { v[j] = v[j] * rstd * gv[j] + bv[j];
;             if (l == NL - 1) *(f32x4*)(outp + (size_t)row * DM + lane * 4 + 256 * j) = v[j];
;             else { u32x2 w; w.x = cvt_pk_bf16(v[j][0], v[j][1]); w.y = cvt_pk_bf16(v[j][2], v[j][3]); *(u32x2*)(XB + (size_t)row * DM + lane * 4 + 256 * j) = w; } }
.LBB0_74:
	v_mov_b32_e32 v48, v45
	v_mov_b32_e32 v49, v46
	v_mov_b32_e32 v50, v44
	v_mov_b32_e32 v51, v47
	v_pk_add_f32 v[48:49], v[48:49], v[50:51]
	v_mov_b32_e32 v50, v41
	v_mov_b32_e32 v51, v42
	v_mov_b32_e32 v52, v40
	v_mov_b32_e32 v53, v43
	v_pk_add_f32 v[50:51], v[50:51], v[52:53]
	v_add_f32_e32 v48, v48, v49
	v_pk_add_f32 v[50:51], v[50:51], v[50:51] op_sel_hi:[0,1]
	v_add_f32_e32 v49, 0, v48
	v_add_f32_e32 v53, v81, v153
	v_add_f32_e32 v55, v154, v155
	v_mov_b32_e32 v52, v32
	v_mov_b32_e32 v54, v33
	v_mov_b32_e32 v50, v34
	v_mov_b32_e32 v48, v35
	v_pk_add_f32 v[52:53], v[52:53], v[54:55]
	v_pk_add_f32 v[48:49], v[50:51], v[48:49]
	v_ashrrev_i32_e32 v81, 31, v80
	v_pk_add_f32 v[48:49], v[52:53], v[48:49]
	s_mov_b64 s[6:7], -1
	v_add_f32_e32 v48, v48, v49
	v_mov_b32_e32 v49, v48
	s_waitcnt lgkmcnt(0)
	s_nop 1
	v_permlane32_swap_b32_e32 v49, v48
	v_add_f32_e32 v48, v48, v49
	v_mov_b32_e32 v49, v48
	s_waitcnt lgkmcnt(0)
	s_nop 1
	v_permlane16_swap_b32_e32 v49, v48
	v_add_f32_e32 v48, v48, v49
	s_waitcnt lgkmcnt(0)
	s_nop 1
	v_add_f32_dpp v48, v48, v48 row_ror:8 row_mask:0xf bank_mask:0xf
	s_waitcnt lgkmcnt(0)
	s_nop 1
	v_add_f32_dpp v48, v48, v48 row_ror:4 row_mask:0xf bank_mask:0xf
	s_waitcnt lgkmcnt(0)
	s_nop 1
	v_add_f32_dpp v48, v48, v48 quad_perm:[2,3,0,1] row_mask:0xf bank_mask:0xf
	s_waitcnt lgkmcnt(0)
	s_nop 1
	v_add_f32_dpp v58, v48, v48 quad_perm:[1,0,3,2] row_mask:0xf bank_mask:0xf
	v_fmamk_f32 v45, v58, 0xba800000, v45
	v_fmamk_f32 v44, v58, 0xba800000, v44
	v_fmamk_f32 v47, v58, 0xba800000, v47
	v_fmac_f32_e32 v46, 0xba800000, v58
	v_fmamk_f32 v57, v58, 0xba800000, v43
	v_fmamk_f32 v56, v58, 0xba800000, v42
	v_pk_mul_f32 v[42:43], v[46:47], v[46:47]
	v_pk_mul_f32 v[48:49], v[44:45], v[44:45]
	v_fmamk_f32 v41, v58, 0xba800000, v41
	v_pk_mov_b32 v[50:51], v[48:49], v[42:43] op_sel:[1,0]
	v_mov_b32_e32 v49, v43
	v_fmac_f32_e32 v40, 0xba800000, v58
	v_pk_add_f32 v[42:43], v[50:51], v[48:49]
	v_pk_mul_f32 v[48:49], v[56:57], v[56:57]
	v_pk_mul_f32 v[50:51], v[40:41], v[40:41]
	v_fmac_f32_e32 v36, 0xba800000, v58
	v_pk_mov_b32 v[52:53], v[50:51], v[48:49] op_sel:[1,0]
	v_mov_b32_e32 v51, v49
	v_pk_add_f32 v[48:49], v[52:53], v[50:51]
	v_fmamk_f32 v52, v58, 0xba800000, v38
	v_fmamk_f32 v37, v58, 0xba800000, v37
	v_mul_f32_e32 v38, v36, v36
	v_fmamk_f32 v53, v58, 0xba800000, v39
	v_pk_fma_f32 v[38:39], v[36:37], v[36:37], v[38:39] op_sel_hi:[1,1,0]
	v_pk_add_f32 v[42:43], v[42:43], v[42:43] op_sel_hi:[0,1]
	v_mul_f32_e32 v38, v52, v52
	v_pk_add_f32 v[50:51], v[48:49], v[48:49] op_sel_hi:[0,1]
	v_pk_fma_f32 v[54:55], v[52:53], v[52:53], v[38:39] op_sel_hi:[1,1,0]
	v_fmamk_f32 v49, v58, 0xba800000, v35
	v_fmamk_f32 v48, v58, 0xba800000, v34
	v_fmamk_f32 v33, v58, 0xba800000, v33
	v_fmac_f32_e32 v32, 0xba800000, v58
	v_mul_f32_e32 v38, v32, v32
	v_mul_f32_e32 v54, v33, v33
	v_mul_f32_e32 v42, v48, v48
	v_mul_f32_e32 v50, v49, v49
	v_pk_add_f32 v[34:35], v[38:39], v[54:55]
	v_pk_add_f32 v[38:39], v[42:43], v[50:51]
	s_nop 0
	v_pk_add_f32 v[34:35], v[34:35], v[38:39]
	s_nop 0
	v_add_f32_e32 v34, v34, v35
	v_mov_b32_e32 v35, v34
	s_waitcnt lgkmcnt(0)
	s_nop 1
	v_permlane32_swap_b32_e32 v35, v34
	v_add_f32_e32 v34, v34, v35
	v_mov_b32_e32 v35, v34
	s_waitcnt lgkmcnt(0)
	s_nop 1
	v_permlane16_swap_b32_e32 v35, v34
	v_add_f32_e32 v34, v34, v35
	s_waitcnt lgkmcnt(0)
	s_nop 1
	v_add_f32_dpp v34, v34, v34 row_ror:8 row_mask:0xf bank_mask:0xf
	s_waitcnt lgkmcnt(0)
	s_nop 1
	v_add_f32_dpp v34, v34, v34 row_ror:4 row_mask:0xf bank_mask:0xf
	s_waitcnt lgkmcnt(0)
	s_nop 1
	v_add_f32_dpp v34, v34, v34 quad_perm:[2,3,0,1] row_mask:0xf bank_mask:0xf
	s_waitcnt lgkmcnt(0)
	s_nop 1
	v_add_f32_dpp v34, v34, v34 quad_perm:[1,0,3,2] row_mask:0xf bank_mask:0xf
	v_mov_b32_e32 v35, 0x3727c5ac
	v_fmamk_f32 v34, v34, 0x3a800000, v35
	v_mul_f32_e32 v35, 0x4b800000, v34
	v_cmp_gt_f32_e32 vcc, s1, v34
	s_nop 1
	v_cndmask_b32_e32 v34, v34, v35, vcc
	v_rsq_f32_e32 v38, v34
	v_lshlrev_b64 v[34:35], 11, v[80:81]
	v_lshl_add_u64 v[50:51], v[64:65], 0, v[34:35]
	v_mul_f32_e32 v34, 0x45800000, v38
	v_cndmask_b32_e32 v54, v38, v34, vcc
	v_pk_mul_f32 v[34:35], v[44:45], v[54:55] op_sel_hi:[1,0]
	v_pk_mul_f32 v[38:39], v[46:47], v[54:55] op_sel_hi:[1,0]
	v_pk_fma_f32 v[42:43], v[0:1], v[34:35], v[8:9]
	v_pk_fma_f32 v[44:45], v[2:3], v[38:39], v[10:11]
	s_and_b64 vcc, exec, s[10:11]
	s_cbranch_vccz .LBB0_76
	v_cvt_pk_bf16_f32 v34, v42, v43
	v_cvt_pk_bf16_f32 v35, v44, v45
	global_store_dwordx2 v[50:51], v[34:35], off
	s_mov_b64 s[6:7], 0

; template <bool GATHER, class Epi>
; __device__ __forceinline__ void gemm_phase(LAS unsigned char* lds, const Sched& S, const Epi& E) {
;     ...
;         const bool has_next = S.next(ui + 1, nxt);
;         const char* nA = cA; const char* nB = cB;
;         if (has_next) { nA = GATHER ? S.A : S.A + (size_t)nxt.pm * tstep + (size_t)nxt.br * S.abr; nB = S.bptr(nxt); }
.LBB0_124:
	s_and_b64 s[10:11], s[6:7], exec
	s_cbranch_scc0 .Lgo_pref_skip
	v_lshl_add_u32 v201, s31, 8, v222
	v_readlane_b32 s10, v252, 26
	v_readlane_b32 s11, v252, 27
	v_lshlrev_b32_e32 v201, 2, v201
	s_nop 4
	global_load_dword v198, v201, s[10:11]
	global_load_dword v199, v201, s[10:11] offset:256
	global_load_dword v200, v201, s[10:11] offset:512
	global_load_dword v201, v201, s[10:11] offset:768

.LBB0_125:
	s_add_i32 s35, 0, 0x10000
	v_add_u32_e32 v140, s35, v231
	ds_read_b128 v[128:131], v140
	ds_read_b128 v[132:135], v140 offset:1024
	ds_read_b128 v[136:139], v140 offset:2048
	ds_read_b128 v[140:143], v140 offset:3072
	s_add_u32 s14, s86, s10
	v_mov_b32_e32 v188, v228
	v_mov_b32_e32 v176, v229
	s_addc_u32 s15, s87, s11
	ds_read_b128 v[144:147], v233
	ds_read_b128 v[148:151], v233 offset:1024
	ds_read_b128 v[152:155], v233 offset:2048
	ds_read_b128 v[156:159], v233 offset:3072
	ds_read_b128 v[160:163], v233 offset:4096
	ds_read_b128 v[164:167], v233 offset:5120
	ds_read_b128 v[168:171], v233 offset:6144
	ds_read_b128 v[172:175], v233 offset:7168
	s_add_i32 s41, s22, 0xc000
	v_lshl_add_u64 v[178:179], s[14:15], 0, v[188:189]
	v_mov_b32_e32 v177, v189
	v_lshl_add_u64 v[178:179], v[178:179], 0, s[44:45]
	s_mov_b32 m0, s41
	v_lshl_add_u64 v[176:177], s[14:15], 0, v[176:177]
	s_add_i32 s42, s22, 0xe000
	global_load_lds_dwordx4 v[178:179], off
	v_lshl_add_u64 v[176:177], v[176:177], 0, s[44:45]
	s_mov_b32 m0, s42
	s_nop 0
	global_load_lds_dwordx4 v[176:177], off
	s_waitcnt lgkmcnt(8)
	s_barrier
	s_waitcnt lgkmcnt(0)
	s_setprio 1
	s_waitcnt lgkmcnt(0)
	v_mfma_f32_16x16x32_bf16 v[124:127], v[128:131], v[144:147], v[124:127]
	v_mfma_f32_16x16x32_bf16 v[120:123], v[136:139], v[144:147], v[120:123]
	v_mfma_f32_16x16x32_bf16 v[116:119], v[128:131], v[152:155], v[116:119]
	v_mfma_f32_16x16x32_bf16 v[112:115], v[136:139], v[152:155], v[112:115]
	v_mfma_f32_16x16x32_bf16 v[108:111], v[128:131], v[160:163], v[108:111]
	v_mfma_f32_16x16x32_bf16 v[104:107], v[136:139], v[160:163], v[104:107]
	v_mfma_f32_16x16x32_bf16 v[100:103], v[128:131], v[168:171], v[100:103]
	v_mfma_f32_16x16x32_bf16 v[96:99], v[136:139], v[168:171], v[96:99]
	v_mfma_f32_16x16x32_bf16 v[124:127], v[132:135], v[148:151], v[124:127]
	v_mfma_f32_16x16x32_bf16 v[120:123], v[140:143], v[148:151], v[120:123]
	v_mfma_f32_16x16x32_bf16 v[116:119], v[132:135], v[156:159], v[116:119]
	v_mfma_f32_16x16x32_bf16 v[112:115], v[140:143], v[156:159], v[112:115]
	v_mfma_f32_16x16x32_bf16 v[108:111], v[132:135], v[164:167], v[108:111]
	v_mfma_f32_16x16x32_bf16 v[104:107], v[140:143], v[164:167], v[104:107]
	v_mfma_f32_16x16x32_bf16 v[100:103], v[132:135], v[172:175], v[100:103]
	v_mfma_f32_16x16x32_bf16 v[96:99], v[140:143], v[172:175], v[96:99]
	s_setprio 0
	s_barrier
	s_add_i32 s36, 0, 0x14000
	s_add_u32 s16, s12, s10
	v_add_u32_e32 v234, s36, v231
	v_mov_b32_e32 v188, v224
	v_mov_b32_e32 v194, v225
	s_addc_u32 s17, s13, s11
	ds_read_b128 v[176:179], v234
	ds_read_b128 v[180:183], v234 offset:1024
	ds_read_b128 v[184:187], v234 offset:2048
	ds_read_b128 v[190:193], v234 offset:3072
	s_add_i32 s35, s35, s21
	v_lshl_add_u64 v[196:197], s[16:17], 0, v[188:189]
	v_mov_b32_e32 v195, v189
	v_lshl_add_u64 v[196:197], v[196:197], 0, s[88:89]
	s_mov_b32 m0, s35
	v_lshl_add_u64 v[194:195], s[16:17], 0, v[194:195]
	global_load_lds_dwordx4 v[196:197], off
	v_lshl_add_u64 v[194:195], v[194:195], 0, s[88:89]
	s_add_i32 m0, s35, 0x2000
	s_nop 0
	global_load_lds_dwordx4 v[194:195], off
	s_barrier
	s_waitcnt lgkmcnt(0)
	s_setprio 1
	s_waitcnt lgkmcnt(0)
	v_mfma_f32_16x16x32_bf16 v[92:95], v[176:179], v[144:147], v[92:95]
	v_mfma_f32_16x16x32_bf16 v[88:91], v[184:187], v[144:147], v[88:91]
	v_mfma_f32_16x16x32_bf16 v[84:87], v[176:179], v[152:155], v[84:87]
	v_mfma_f32_16x16x32_bf16 v[80:83], v[184:187], v[152:155], v[80:83]
	v_mfma_f32_16x16x32_bf16 v[76:79], v[176:179], v[160:163], v[76:79]
	v_mfma_f32_16x16x32_bf16 v[72:75], v[184:187], v[160:163], v[72:75]
	v_mfma_f32_16x16x32_bf16 v[68:71], v[176:179], v[168:171], v[68:71]
	v_mfma_f32_16x16x32_bf16 v[64:67], v[184:187], v[168:171], v[64:67]
	v_mfma_f32_16x16x32_bf16 v[92:95], v[180:183], v[148:151], v[92:95]
	v_mfma_f32_16x16x32_bf16 v[88:91], v[190:193], v[148:151], v[88:91]
	v_mfma_f32_16x16x32_bf16 v[84:87], v[180:183], v[156:159], v[84:87]
	v_mfma_f32_16x16x32_bf16 v[80:83], v[190:193], v[156:159], v[80:83]
	v_mfma_f32_16x16x32_bf16 v[76:79], v[180:183], v[164:167], v[76:79]
	v_mfma_f32_16x16x32_bf16 v[72:75], v[190:193], v[164:167], v[72:75]
	v_mfma_f32_16x16x32_bf16 v[68:71], v[180:183], v[172:175], v[68:71]
	v_mfma_f32_16x16x32_bf16 v[64:67], v[190:193], v[172:175], v[64:67]
	s_setprio 0
	v_mov_b32_e32 v188, v226
	v_mov_b32_e32 v194, v227
	s_barrier
	ds_read_b128 v[144:147], v233 offset:16384
	ds_read_b128 v[148:151], v233 offset:17408
	ds_read_b128 v[152:155], v233 offset:18432
	ds_read_b128 v[156:159], v233 offset:19456
	ds_read_b128 v[160:163], v233 offset:20480
	ds_read_b128 v[164:167], v233 offset:21504
	ds_read_b128 v[168:171], v233 offset:22528
	ds_read_b128 v[172:175], v233 offset:23552
	v_mov_b32_e32 v195, v189
	v_lshl_add_u64 v[196:197], s[14:15], 0, v[188:189]
	s_mov_b32 m0, s22
	v_lshl_add_u64 v[196:197], v[196:197], 0, s[46:47]
	v_lshl_add_u64 v[194:195], s[14:15], 0, v[194:195]
	global_load_lds_dwordx4 v[196:197], off
	v_lshl_add_u64 v[194:195], v[194:195], 0, s[46:47]
	s_mov_b32 m0, s25
	s_nop 0
	global_load_lds_dwordx4 v[194:195], off
	s_barrier
	s_waitcnt lgkmcnt(0)
	s_setprio 1
	s_waitcnt lgkmcnt(0)
	v_mfma_f32_16x16x32_bf16 v[60:63], v[128:131], v[144:147], v[60:63]
	v_mfma_f32_16x16x32_bf16 v[56:59], v[136:139], v[144:147], v[56:59]
	v_mfma_f32_16x16x32_bf16 v[52:55], v[128:131], v[152:155], v[52:55]
	v_mfma_f32_16x16x32_bf16 v[48:51], v[136:139], v[152:155], v[48:51]
	v_mfma_f32_16x16x32_bf16 v[44:47], v[128:131], v[160:163], v[44:47]
	v_mfma_f32_16x16x32_bf16 v[40:43], v[136:139], v[160:163], v[40:43]
	v_mfma_f32_16x16x32_bf16 v[36:39], v[128:131], v[168:171], v[36:39]
	v_mfma_f32_16x16x32_bf16 v[32:35], v[136:139], v[168:171], v[32:35]
	v_mfma_f32_16x16x32_bf16 v[60:63], v[132:135], v[148:151], v[60:63]
	v_mfma_f32_16x16x32_bf16 v[56:59], v[140:143], v[148:151], v[56:59]
	v_mfma_f32_16x16x32_bf16 v[52:55], v[132:135], v[156:159], v[52:55]
	v_mfma_f32_16x16x32_bf16 v[48:51], v[140:143], v[156:159], v[48:51]
	v_mfma_f32_16x16x32_bf16 v[44:47], v[132:135], v[164:167], v[44:47]
	v_mfma_f32_16x16x32_bf16 v[40:43], v[140:143], v[164:167], v[40:43]
	v_mfma_f32_16x16x32_bf16 v[36:39], v[132:135], v[172:175], v[36:39]
	v_mfma_f32_16x16x32_bf16 v[32:35], v[140:143], v[172:175], v[32:35]
	s_setprio 0
	s_barrier
	v_mov_b32_e32 v188, v224
	v_mov_b32_e32 v128, v225
	s_add_i32 s35, s36, s21
	v_lshl_add_u64 v[130:131], s[16:17], 0, v[188:189]
	v_mov_b32_e32 v129, v189
	v_lshl_add_u64 v[130:131], v[130:131], 0, s[48:49]
	s_mov_b32 m0, s35
	v_lshl_add_u64 v[128:129], s[16:17], 0, v[128:129]
	s_add_i32 s36, s35, 0x2000
	global_load_lds_dwordx4 v[130:131], off
	v_lshl_add_u64 v[128:129], v[128:129], 0, s[48:49]
	s_mov_b32 m0, s36
	s_nop 0
	global_load_lds_dwordx4 v[128:129], off
	s_waitcnt vmcnt(6)
	s_barrier
	s_setprio 1
	v_mfma_f32_16x16x32_bf16 v[28:31], v[176:179], v[144:147], v[28:31]
	v_mfma_f32_16x16x32_bf16 v[24:27], v[184:187], v[144:147], v[24:27]
	v_mfma_f32_16x16x32_bf16 v[20:23], v[176:179], v[152:155], v[20:23]
	v_mfma_f32_16x16x32_bf16 v[16:19], v[184:187], v[152:155], v[16:19]
	v_mfma_f32_16x16x32_bf16 v[12:15], v[176:179], v[160:163], v[12:15]
	v_mfma_f32_16x16x32_bf16 v[8:11], v[184:187], v[160:163], v[8:11]
	v_mfma_f32_16x16x32_bf16 v[4:7], v[176:179], v[168:171], v[4:7]
	v_mfma_f32_16x16x32_bf16 v[0:3], v[184:187], v[168:171], v[0:3]
	v_mfma_f32_16x16x32_bf16 v[28:31], v[180:183], v[148:151], v[28:31]
	v_mfma_f32_16x16x32_bf16 v[24:27], v[190:193], v[148:151], v[24:27]
	v_mfma_f32_16x16x32_bf16 v[20:23], v[180:183], v[156:159], v[20:23]
	v_mfma_f32_16x16x32_bf16 v[16:19], v[190:193], v[156:159], v[16:19]
	v_mfma_f32_16x16x32_bf16 v[12:15], v[180:183], v[164:167], v[12:15]
	v_mfma_f32_16x16x32_bf16 v[8:11], v[190:193], v[164:167], v[8:11]
	v_mfma_f32_16x16x32_bf16 v[4:7], v[180:183], v[172:175], v[4:7]
	v_mfma_f32_16x16x32_bf16 v[0:3], v[190:193], v[172:175], v[0:3]
	s_setprio 0
	s_add_i32 s40, 0, 0x18000
	v_add_u32_e32 v235, s40, v231
	s_barrier
	ds_read_b128 v[128:131], v235
	ds_read_b128 v[132:135], v235 offset:1024
	ds_read_b128 v[136:139], v235 offset:2048
	ds_read_b128 v[140:143], v235 offset:3072
	v_mov_b32_e32 v188, v228
	v_mov_b32_e32 v176, v229
	ds_read_b128 v[144:147], v233 offset:32768
	ds_read_b128 v[148:151], v233 offset:33792
	ds_read_b128 v[152:155], v233 offset:34816
	ds_read_b128 v[156:159], v233 offset:35840
	ds_read_b128 v[160:163], v233 offset:36864
	ds_read_b128 v[164:167], v233 offset:37888
	ds_read_b128 v[168:171], v233 offset:38912
	ds_read_b128 v[172:175], v233 offset:39936
	v_mov_b32_e32 v177, v189
	v_lshl_add_u64 v[178:179], s[14:15], 0, v[188:189]
	s_mov_b32 m0, s26
	v_lshl_add_u64 v[178:179], v[178:179], 0, s[46:47]
	v_lshl_add_u64 v[176:177], s[14:15], 0, v[176:177]
	global_load_lds_dwordx4 v[178:179], off
	v_lshl_add_u64 v[176:177], v[176:177], 0, s[46:47]
	s_mov_b32 m0, s27
	s_nop 0
	global_load_lds_dwordx4 v[176:177], off
	s_waitcnt lgkmcnt(8)
	s_barrier
	s_waitcnt lgkmcnt(0)
	s_setprio 1
	s_waitcnt lgkmcnt(0)
	v_mfma_f32_16x16x32_bf16 v[124:127], v[128:131], v[144:147], v[124:127]
	v_mfma_f32_16x16x32_bf16 v[120:123], v[136:139], v[144:147], v[120:123]
	v_mfma_f32_16x16x32_bf16 v[116:119], v[128:131], v[152:155], v[116:119]
	v_mfma_f32_16x16x32_bf16 v[112:115], v[136:139], v[152:155], v[112:115]
	v_mfma_f32_16x16x32_bf16 v[108:111], v[128:131], v[160:163], v[108:111]
	v_mfma_f32_16x16x32_bf16 v[104:107], v[136:139], v[160:163], v[104:107]
	v_mfma_f32_16x16x32_bf16 v[100:103], v[128:131], v[168:171], v[100:103]
	v_mfma_f32_16x16x32_bf16 v[96:99], v[136:139], v[168:171], v[96:99]
	v_mfma_f32_16x16x32_bf16 v[124:127], v[132:135], v[148:151], v[124:127]
	v_mfma_f32_16x16x32_bf16 v[120:123], v[140:143], v[148:151], v[120:123]
	v_mfma_f32_16x16x32_bf16 v[116:119], v[132:135], v[156:159], v[116:119]
	v_mfma_f32_16x16x32_bf16 v[112:115], v[140:143], v[156:159], v[112:115]
	v_mfma_f32_16x16x32_bf16 v[108:111], v[132:135], v[164:167], v[108:111]
	v_mfma_f32_16x16x32_bf16 v[104:107], v[140:143], v[164:167], v[104:107]
	v_mfma_f32_16x16x32_bf16 v[100:103], v[132:135], v[172:175], v[100:103]
	v_mfma_f32_16x16x32_bf16 v[96:99], v[140:143], v[172:175], v[96:99]
	s_setprio 0
	s_barrier
	s_add_i32 s43, 0, 0x1c000
	v_add_u32_e32 v236, s43, v231
	v_mov_b32_e32 v188, v224
	v_mov_b32_e32 v194, v225
	ds_read_b128 v[176:179], v236
	ds_read_b128 v[180:183], v236 offset:1024
	ds_read_b128 v[184:187], v236 offset:2048
	ds_read_b128 v[190:193], v236 offset:3072
	s_add_i32 s40, s40, s21
	v_lshl_add_u64 v[196:197], s[16:17], 0, v[188:189]
	v_mov_b32_e32 v195, v189
	v_lshl_add_u64 v[196:197], v[196:197], 0, s[2:3]
	s_mov_b32 m0, s40
	v_lshl_add_u64 v[194:195], s[16:17], 0, v[194:195]
	s_add_i32 s37, s40, 0x2000
	global_load_lds_dwordx4 v[196:197], off
	v_lshl_add_u64 v[194:195], v[194:195], 0, s[2:3]
	s_mov_b32 m0, s37
	s_nop 0
	global_load_lds_dwordx4 v[194:195], off
	s_barrier
	s_waitcnt lgkmcnt(0)
	s_setprio 1
	s_waitcnt lgkmcnt(0)
	v_mfma_f32_16x16x32_bf16 v[92:95], v[176:179], v[144:147], v[92:95]
	v_mfma_f32_16x16x32_bf16 v[88:91], v[184:187], v[144:147], v[88:91]
	v_mfma_f32_16x16x32_bf16 v[84:87], v[176:179], v[152:155], v[84:87]
	v_mfma_f32_16x16x32_bf16 v[80:83], v[184:187], v[152:155], v[80:83]
	v_mfma_f32_16x16x32_bf16 v[76:79], v[176:179], v[160:163], v[76:79]
	v_mfma_f32_16x16x32_bf16 v[72:75], v[184:187], v[160:163], v[72:75]
	v_mfma_f32_16x16x32_bf16 v[68:71], v[176:179], v[168:171], v[68:71]
	v_mfma_f32_16x16x32_bf16 v[64:67], v[184:187], v[168:171], v[64:67]
	v_mfma_f32_16x16x32_bf16 v[92:95], v[180:183], v[148:151], v[92:95]
	v_mfma_f32_16x16x32_bf16 v[88:91], v[190:193], v[148:151], v[88:91]
	v_mfma_f32_16x16x32_bf16 v[84:87], v[180:183], v[156:159], v[84:87]
	v_mfma_f32_16x16x32_bf16 v[80:83], v[190:193], v[156:159], v[80:83]
	v_mfma_f32_16x16x32_bf16 v[76:79], v[180:183], v[164:167], v[76:79]
	v_mfma_f32_16x16x32_bf16 v[72:75], v[190:193], v[164:167], v[72:75]
	v_mfma_f32_16x16x32_bf16 v[68:71], v[180:183], v[172:175], v[68:71]
	v_mfma_f32_16x16x32_bf16 v[64:67], v[190:193], v[172:175], v[64:67]
	s_setprio 0
	v_mov_b32_e32 v188, v226
	v_mov_b32_e32 v194, v227
	s_barrier
	ds_read_b128 v[144:147], v233 offset:49152
	ds_read_b128 v[148:151], v233 offset:50176
	ds_read_b128 v[152:155], v233 offset:51200
	ds_read_b128 v[156:159], v233 offset:52224
	ds_read_b128 v[160:163], v233 offset:53248
	ds_read_b128 v[164:167], v233 offset:54272
	ds_read_b128 v[168:171], v233 offset:55296
	ds_read_b128 v[172:175], v233 offset:56320
	v_mov_b32_e32 v195, v189
	v_lshl_add_u64 v[196:197], s[14:15], 0, v[188:189]
	s_mov_b32 m0, s28
	v_lshl_add_u64 v[196:197], v[196:197], 0, s[50:51]
	v_lshl_add_u64 v[194:195], s[14:15], 0, v[194:195]
	global_load_lds_dwordx4 v[196:197], off
	v_lshl_add_u64 v[194:195], v[194:195], 0, s[50:51]
	s_mov_b32 m0, s29
	s_nop 0
	global_load_lds_dwordx4 v[194:195], off
	s_barrier
	s_waitcnt lgkmcnt(0)
	s_setprio 1
	s_waitcnt lgkmcnt(0)
	v_mfma_f32_16x16x32_bf16 v[60:63], v[128:131], v[144:147], v[60:63]
	v_mfma_f32_16x16x32_bf16 v[56:59], v[136:139], v[144:147], v[56:59]
	v_mfma_f32_16x16x32_bf16 v[52:55], v[128:131], v[152:155], v[52:55]
	v_mfma_f32_16x16x32_bf16 v[48:51], v[136:139], v[152:155], v[48:51]
	v_mfma_f32_16x16x32_bf16 v[44:47], v[128:131], v[160:163], v[44:47]
	v_mfma_f32_16x16x32_bf16 v[40:43], v[136:139], v[160:163], v[40:43]
	v_mfma_f32_16x16x32_bf16 v[36:39], v[128:131], v[168:171], v[36:39]
	v_mfma_f32_16x16x32_bf16 v[32:35], v[136:139], v[168:171], v[32:35]
	v_mfma_f32_16x16x32_bf16 v[60:63], v[132:135], v[148:151], v[60:63]
	v_mfma_f32_16x16x32_bf16 v[56:59], v[140:143], v[148:151], v[56:59]
	v_mfma_f32_16x16x32_bf16 v[52:55], v[132:135], v[156:159], v[52:55]
	v_mfma_f32_16x16x32_bf16 v[48:51], v[140:143], v[156:159], v[48:51]
	v_mfma_f32_16x16x32_bf16 v[44:47], v[132:135], v[164:167], v[44:47]
	v_mfma_f32_16x16x32_bf16 v[40:43], v[140:143], v[164:167], v[40:43]
	v_mfma_f32_16x16x32_bf16 v[36:39], v[132:135], v[172:175], v[36:39]
	v_mfma_f32_16x16x32_bf16 v[32:35], v[140:143], v[172:175], v[32:35]
	s_setprio 0
	s_barrier
	v_mov_b32_e32 v188, v224
	v_mov_b32_e32 v128, v225
	s_add_i32 s14, s43, s21
	v_lshl_add_u64 v[130:131], s[16:17], 0, v[188:189]
	v_mov_b32_e32 v129, v189
	v_lshl_add_u64 v[130:131], v[130:131], 0, s[52:53]
	s_mov_b32 m0, s14
	v_lshl_add_u64 v[128:129], s[16:17], 0, v[128:129]
	s_add_i32 s15, s14, 0x2000
	global_load_lds_dwordx4 v[130:131], off
	v_lshl_add_u64 v[128:129], v[128:129], 0, s[52:53]
	s_mov_b32 m0, s15
	s_nop 0
	global_load_lds_dwordx4 v[128:129], off
	s_waitcnt vmcnt(6)
	s_barrier
	s_setprio 1
	v_mfma_f32_16x16x32_bf16 v[28:31], v[176:179], v[144:147], v[28:31]
	v_mfma_f32_16x16x32_bf16 v[24:27], v[184:187], v[144:147], v[24:27]
	v_mfma_f32_16x16x32_bf16 v[20:23], v[176:179], v[152:155], v[20:23]
	v_mfma_f32_16x16x32_bf16 v[16:19], v[184:187], v[152:155], v[16:19]
	v_mfma_f32_16x16x32_bf16 v[12:15], v[176:179], v[160:163], v[12:15]
	v_mfma_f32_16x16x32_bf16 v[8:11], v[184:187], v[160:163], v[8:11]
	v_mfma_f32_16x16x32_bf16 v[4:7], v[176:179], v[168:171], v[4:7]
	v_mfma_f32_16x16x32_bf16 v[0:3], v[184:187], v[168:171], v[0:3]
	v_mfma_f32_16x16x32_bf16 v[28:31], v[180:183], v[148:151], v[28:31]
	v_mfma_f32_16x16x32_bf16 v[24:27], v[190:193], v[148:151], v[24:27]
	v_mfma_f32_16x16x32_bf16 v[20:23], v[180:183], v[156:159], v[20:23]
	v_mfma_f32_16x16x32_bf16 v[16:19], v[190:193], v[156:159], v[16:19]
	v_mfma_f32_16x16x32_bf16 v[12:15], v[180:183], v[164:167], v[12:15]
	v_mfma_f32_16x16x32_bf16 v[8:11], v[190:193], v[164:167], v[8:11]
	v_mfma_f32_16x16x32_bf16 v[4:7], v[180:183], v[172:175], v[4:7]
	v_mfma_f32_16x16x32_bf16 v[0:3], v[190:193], v[172:175], v[0:3]
	s_setprio 0
	s_add_i32 s9, s9, 2
	s_add_u32 s10, s10, 0x100
	s_addc_u32 s11, s11, 0
	s_cmp_lt_u32 s9, 12
	s_barrier
	s_cbranch_scc1 .LBB0_125
	v_add_u32_e32 v128, 0, v231
	v_add_u32_e32 v128, 0x10000, v128
	ds_read_b128 v[140:143], v128
	ds_read_b128 v[144:147], v128 offset:1024
	ds_read_b128 v[148:151], v128 offset:2048
	ds_read_b128 v[152:155], v128 offset:3072
	v_readlane_b32 s10, v252, 14
	v_mov_b32_e32 v128, v228
	v_mov_b32_e32 v129, v229
	s_mov_b32 m0, s41
	v_readlane_b32 s11, v252, 15
	ds_read_b128 v[180:183], v233
	ds_read_b128 v[184:187], v233 offset:1024
	ds_read_b128 v[172:175], v233 offset:2048
	ds_read_b128 v[176:179], v233 offset:3072
	ds_read_b128 v[164:167], v233 offset:4096
	ds_read_b128 v[168:171], v233 offset:5120
	ds_read_b128 v[156:159], v233 offset:6144
	ds_read_b128 v[160:163], v233 offset:7168
	s_nop 0
	global_load_lds_dwordx4 v128, s[10:11]
	s_mov_b32 m0, s42
	s_nop 0
	global_load_lds_dwordx4 v129, s[10:11]
	s_waitcnt lgkmcnt(8)
	s_barrier
	s_waitcnt lgkmcnt(0)
	s_setprio 1
	s_waitcnt lgkmcnt(0)
	v_mfma_f32_16x16x32_bf16 v[124:127], v[140:143], v[180:183], v[124:127]
	v_mfma_f32_16x16x32_bf16 v[120:123], v[148:151], v[180:183], v[120:123]
	v_mfma_f32_16x16x32_bf16 v[116:119], v[140:143], v[172:175], v[116:119]
	v_mfma_f32_16x16x32_bf16 v[112:115], v[148:151], v[172:175], v[112:115]
	v_mfma_f32_16x16x32_bf16 v[108:111], v[140:143], v[164:167], v[108:111]
	v_mfma_f32_16x16x32_bf16 v[104:107], v[148:151], v[164:167], v[104:107]
	v_mfma_f32_16x16x32_bf16 v[100:103], v[140:143], v[156:159], v[100:103]
	v_mfma_f32_16x16x32_bf16 v[96:99], v[148:151], v[156:159], v[96:99]
	v_mfma_f32_16x16x32_bf16 v[124:127], v[144:147], v[184:187], v[124:127]
	v_mfma_f32_16x16x32_bf16 v[120:123], v[152:155], v[184:187], v[120:123]
	v_mfma_f32_16x16x32_bf16 v[116:119], v[144:147], v[176:179], v[116:119]
	v_mfma_f32_16x16x32_bf16 v[128:131], v[152:155], v[176:179], v[112:115]
	v_mfma_f32_16x16x32_bf16 v[108:111], v[144:147], v[168:171], v[108:111]
	v_mfma_f32_16x16x32_bf16 v[132:135], v[152:155], v[168:171], v[104:107]
	v_mfma_f32_16x16x32_bf16 v[100:103], v[144:147], v[160:163], v[100:103]
	v_mfma_f32_16x16x32_bf16 v[136:139], v[152:155], v[160:163], v[96:99]
	s_setprio 0
	s_barrier
	s_andn2_b64 vcc, exec, s[6:7]
	s_cbranch_vccnz .LBB0_117
	v_lshl_add_u32 v226, v198, 11, v223
	v_lshl_add_u32 v227, v199, 11, v223
	v_lshl_add_u32 v228, v200, 11, v223
	v_lshl_add_u32 v229, v201, 11, v223
	s_branch .LBB0_117

; __device__ __forceinline__ unsigned cvt_pk_bf16(float lo, float hi) { unsigned r; asm("v_cvt_pk_bf16_f32 %0, %1, %2" : "=v"(r) : "v"(lo), "v"(hi)); return r; }
; __device__ __forceinline__ float bf_lo(unsigned w) { return __uint_as_float(w << 16); }
; __device__ __forceinline__ float bf_hi(unsigned w) { return __uint_as_float(w & 0xffff0000u); }
; __device__ __forceinline__ float wave_sum(float v) {
; #pragma unroll
;     for (int o = 32; o >= 1; o >>= 1) v += __shfl_xor(v, o);
;     return v;
; __device__ void phase_ln1_router(const Params& p, int l, LAS unsigned char* lds) {
;     ...
;         f32x4 v[4]; float s = 0.f;
; #pragma unroll
;         for (int j = 0; j < 4; ++j) { const u32x2 w = raw[j]; v[j] = (f32x4){bf_lo(w.x), bf_hi(w.x), bf_lo(w.y), bf_hi(w.y)}; s += (v[j][0] + v[j][1]) + (v[j][2] + v[j][3]); }
;         if (row + rstride < SEQ) {
; #pragma unroll
;             for (int j = 0; j < 4; ++j) raw[j] = *(const u32x2*)(XP + (size_t)(row + rstride) * DM + lane * 4 + 256 * j); }
;         const float mean = wave_sum(s) * (1.0f / 1024.0f); float q = 0.f;
; #pragma unroll
;         for (int j = 0; j < 4; ++j) { v[j] = v[j] - mean; q += (v[j][0] * v[j][0] + v[j][1] * v[j][1]) + (v[j][2] * v[j][2] + v[j][3] * v[j][3]); }
;         const float rstd = rsqrtf(wave_sum(q) * (1.0f / 1024.0f) + 1e-5f);
; #pragma unroll
;         for (int j = 0; j < 4; ++j) { v[j] = v[j] * rstd * gv[j] + bv[j];
;             u32x2 w; w.x = cvt_pk_bf16(v[j][0], v[j][1]); w.y = cvt_pk_bf16(v[j][2], v[j][3]); *(u32x2*)(XB + (size_t)row * DM + lane * 4 + 256 * j) = w; }
.LBB0_316:
	s_or_b64 exec, exec, s[20:21]
	v_lshlrev_b32_e32 v56, 16, v54
	v_and_b32_e32 v57, 0xffff0000, v54
	v_lshlrev_b32_e32 v54, 16, v55
	v_and_b32_e32 v55, 0xffff0000, v55
	v_add_f32_e32 v33, v56, v57
	v_add_f32_e32 v58, v54, v55
	v_add_f32_e32 v33, v33, v58
	v_lshlrev_b32_e32 v58, 16, v52
	v_and_b32_e32 v59, 0xffff0000, v52
	v_lshlrev_b32_e32 v52, 16, v53
	v_and_b32_e32 v53, 0xffff0000, v53
	v_add_f32_e32 v60, v58, v59
	v_add_f32_e32 v61, v52, v53
	v_add_f32_e32 v33, 0, v33
	v_add_f32_e32 v60, v60, v61
	v_lshlrev_b32_e32 v72, 16, v50
	v_and_b32_e32 v73, 0xffff0000, v50
	v_lshlrev_b32_e32 v50, 16, v51
	v_and_b32_e32 v51, 0xffff0000, v51
	v_add_f32_e32 v33, v33, v60
	v_add_f32_e32 v60, v72, v73
	v_add_f32_e32 v61, v50, v51
	v_add_f32_e32 v60, v60, v61
	v_lshlrev_b32_e32 v74, 16, v48
	v_and_b32_e32 v75, 0xffff0000, v48
	v_lshlrev_b32_e32 v48, 16, v49
	v_and_b32_e32 v49, 0xffff0000, v49
	v_add_f32_e32 v33, v33, v60
	v_add_f32_e32 v60, v74, v75
	v_add_f32_e32 v61, v48, v49
	v_add_f32_e32 v60, v60, v61
	v_add_f32_e32 v33, v33, v60
	v_mov_b32_e32 v60, v33
	s_mov_b32 s20, 0x1a601000
	s_waitcnt lgkmcnt(0)
	s_nop 1
	v_permlane32_swap_b32_e32 v60, v33
	v_add_f32_e32 v33, v33, v60
	v_mov_b32_e32 v60, v33
	s_waitcnt lgkmcnt(0)
	s_nop 1
	v_permlane16_swap_b32_e32 v60, v33
	v_add_f32_e32 v33, v33, v60
	s_waitcnt lgkmcnt(0)
	s_nop 1
	v_add_f32_dpp v33, v33, v33 row_ror:8 row_mask:0xf bank_mask:0xf
	s_waitcnt lgkmcnt(0)
	s_nop 1
	v_add_f32_dpp v33, v33, v33 row_ror:4 row_mask:0xf bank_mask:0xf
	s_waitcnt lgkmcnt(0)
	s_nop 1
	v_add_f32_dpp v33, v33, v33 quad_perm:[2,3,0,1] row_mask:0xf bank_mask:0xf
	s_waitcnt lgkmcnt(0)
	s_nop 1
	v_add_f32_dpp v33, v33, v33 quad_perm:[1,0,3,2] row_mask:0xf bank_mask:0xf
	v_fmac_f32_e32 v57, 0xba800000, v33
	v_fmac_f32_e32 v56, 0xba800000, v33
	v_fmac_f32_e32 v55, 0xba800000, v33
	v_fmac_f32_e32 v54, 0xba800000, v33
	v_pk_mul_f32 v[60:61], v[54:55], v[54:55]
	v_pk_mul_f32 v[62:63], v[56:57], v[56:57]
	v_fmac_f32_e32 v59, 0xba800000, v33
	v_pk_mov_b32 v[76:77], v[62:63], v[60:61] op_sel:[1,0]
	v_mov_b32_e32 v63, v61
	v_pk_add_f32 v[60:61], v[76:77], v[62:63]
	v_fmac_f32_e32 v58, 0xba800000, v33
	v_fmac_f32_e32 v53, 0xba800000, v33
	v_fmac_f32_e32 v52, 0xba800000, v33
	v_pk_add_f32 v[60:61], v[60:61], v[60:61] op_sel_hi:[0,1]
	v_pk_mul_f32 v[62:63], v[52:53], v[52:53]
	v_pk_mul_f32 v[76:77], v[58:59], v[58:59]
	v_fmac_f32_e32 v72, 0xba800000, v33
	v_pk_mov_b32 v[78:79], v[76:77], v[62:63] op_sel:[1,0]
	v_mov_b32_e32 v77, v63
	v_fmac_f32_e32 v73, 0xba800000, v33
	v_fmac_f32_e32 v50, 0xba800000, v33
	v_mul_f32_e32 v60, v72, v72
	v_pk_add_f32 v[62:63], v[78:79], v[76:77]
	v_fmac_f32_e32 v51, 0xba800000, v33
	v_pk_fma_f32 v[76:77], v[72:73], v[72:73], v[60:61] op_sel_hi:[1,1,0]
	v_mul_f32_e32 v60, v50, v50
	v_pk_add_f32 v[62:63], v[62:63], v[62:63] op_sel_hi:[0,1]
	v_pk_fma_f32 v[78:79], v[50:51], v[50:51], v[60:61] op_sel_hi:[1,1,0]
	v_fmac_f32_e32 v49, 0xba800000, v33
	v_fmac_f32_e32 v48, 0xba800000, v33
	v_fmac_f32_e32 v75, 0xba800000, v33
	v_fmac_f32_e32 v74, 0xba800000, v33
	v_mul_f32_e32 v76, v74, v74
	v_mul_f32_e32 v78, v75, v75
	v_mul_f32_e32 v60, v48, v48
	v_mul_f32_e32 v62, v49, v49
	v_pk_add_f32 v[76:77], v[76:77], v[78:79]
	v_pk_add_f32 v[60:61], v[60:61], v[62:63]
	v_lshl_add_u64 v[78:79], s[86:87], 0, v[34:35]
	v_pk_add_f32 v[60:61], v[76:77], v[60:61]
	s_nop 0
	v_add_f32_e32 v33, v60, v61
	v_mov_b32_e32 v60, v33
	s_waitcnt lgkmcnt(0)
	s_nop 1
	v_permlane32_swap_b32_e32 v60, v33
	v_add_f32_e32 v33, v33, v60
	v_mov_b32_e32 v60, v33
	s_waitcnt lgkmcnt(0)
	s_nop 1
	v_permlane16_swap_b32_e32 v60, v33
	v_add_f32_e32 v33, v33, v60
	s_waitcnt lgkmcnt(0)
	s_nop 1
	v_add_f32_dpp v33, v33, v33 row_ror:8 row_mask:0xf bank_mask:0xf
	s_waitcnt lgkmcnt(0)
	s_nop 1
	v_add_f32_dpp v33, v33, v33 row_ror:4 row_mask:0xf bank_mask:0xf
	s_waitcnt lgkmcnt(0)
	s_nop 1
	v_add_f32_dpp v33, v33, v33 quad_perm:[2,3,0,1] row_mask:0xf bank_mask:0xf
	s_waitcnt lgkmcnt(0)
	s_nop 1
	v_add_f32_dpp v33, v33, v33 quad_perm:[1,0,3,2] row_mask:0xf bank_mask:0xf
	v_mov_b32_e32 v60, 0x3727c5ac
	v_fmamk_f32 v33, v33, 0x3a800000, v60
	v_cmp_gt_f32_e32 vcc, s1, v33
	v_mul_f32_e32 v60, 0x4b800000, v33
	s_nop 0
	v_cndmask_b32_e32 v33, v33, v60, vcc
	v_rsq_f32_e32 v33, v33
	s_nop 0
	v_mul_f32_e32 v60, 0x45800000, v33
	v_cndmask_b32_e32 v76, v33, v60, vcc
	v_pk_mul_f32 v[56:57], v[56:57], v[76:77] op_sel_hi:[1,0]
	v_pk_mul_f32 v[54:55], v[54:55], v[76:77] op_sel_hi:[1,0]
	v_add_co_u32_e32 v78, vcc, s20, v78
	v_pk_fma_f32 v[60:61], v[30:31], v[54:55], v[26:27]
	v_pk_fma_f32 v[62:63], v[28:29], v[56:57], v[24:25]
	v_cvt_pk_bf16_f32 v55, v60, v61
	v_addc_co_u32_e32 v79, vcc, 0, v79, vcc
	v_cvt_pk_bf16_f32 v54, v62, v63
	global_store_dwordx2 v[78:79], v[54:55], off
	v_pk_mul_f32 v[54:55], v[58:59], v[76:77] op_sel_hi:[1,0]
	v_pk_mul_f32 v[52:53], v[52:53], v[76:77] op_sel_hi:[1,0]
	v_pk_fma_f32 v[54:55], v[20:21], v[54:55], v[16:17]
	v_pk_fma_f32 v[52:53], v[22:23], v[52:53], v[18:19]
	v_cvt_pk_bf16_f32 v56, v54, v55
	v_pk_mul_f32 v[58:59], v[72:73], v[76:77] op_sel_hi:[1,0]
	v_cvt_pk_bf16_f32 v57, v52, v53
	v_pk_mul_f32 v[50:51], v[50:51], v[76:77] op_sel_hi:[1,0]
	global_store_dwordx2 v[78:79], v[56:57], off offset:512
	v_pk_fma_f32 v[56:57], v[14:15], v[50:51], v[10:11]
	v_pk_fma_f32 v[58:59], v[12:13], v[58:59], v[8:9]
	v_cvt_pk_bf16_f32 v51, v56, v57
	v_pk_mul_f32 v[48:49], v[48:49], v[76:77] op_sel_hi:[1,0]
	v_cvt_pk_bf16_f32 v50, v58, v59
	global_store_dwordx2 v[78:79], v[50:51], off offset:1024
	v_pk_mul_f32 v[50:51], v[74:75], v[76:77] op_sel_hi:[1,0]
	v_pk_fma_f32 v[48:49], v[6:7], v[48:49], v[2:3]
	v_pk_fma_f32 v[50:51], v[4:5], v[50:51], v[0:1]
	v_cvt_pk_bf16_f32 v73, v48, v49
	s_mov_b32 s20, 0x3fb8aa3b
	v_cvt_pk_bf16_f32 v72, v50, v51
	global_store_dwordx2 v[78:79], v[72:73], off offset:1536
	ds_read_b128 v[72:75], v70
	s_waitcnt lgkmcnt(0)
; #define LAS __attribute__((address_space(3)))
; __device__ void phase_ln1_router(const Params& p, int l, LAS unsigned char* lds) {
;     ...
;         float a16[16];
; #pragma unroll
;         for (int e = 0; e < 16; ++e) { float a = 0.f;
; #pragma unroll
;             for (int j = 0; j < 4; ++j) { const f32x4 w = *(const LAS f32x4*)(rw_s + e * RWP + lane * 4 + 256 * j); a += v[j][0] * w[0] + v[j][1] * w[1] + v[j][2] * w[2] + v[j][3] * w[3]; }
;             a16[e] = a; }
	v_mul_f32_e32 v33, v73, v63
	v_fmac_f32_e32 v33, v72, v62
	v_fmac_f32_e32 v33, v74, v60
	v_fmac_f32_e32 v33, v75, v61
	ds_read_b128 v[72:75], v70 offset:1024
	v_add_f32_e32 v33, 0, v33
	s_waitcnt lgkmcnt(0)
	v_mul_f32_e32 v71, v73, v55
	v_fmac_f32_e32 v71, v72, v54
	v_fmac_f32_e32 v71, v74, v52
	v_fmac_f32_e32 v71, v75, v53
	ds_read_b128 v[72:75], v70 offset:2048
	v_add_f32_e32 v33, v71, v33
	s_waitcnt lgkmcnt(0)
	v_mul_f32_e32 v71, v73, v59
	v_fmac_f32_e32 v71, v72, v58
	v_fmac_f32_e32 v71, v74, v56
	v_fmac_f32_e32 v71, v75, v57
	ds_read_b128 v[72:75], v70 offset:3072
	v_add_f32_e32 v33, v71, v33
	s_waitcnt lgkmcnt(0)
	v_mul_f32_e32 v71, v73, v51
	v_fmac_f32_e32 v71, v72, v50
	v_fmac_f32_e32 v71, v74, v48
	v_fmac_f32_e32 v71, v75, v49
	ds_read_b128 v[72:75], v70 offset:4112
	v_add_f32_e32 v33, v71, v33
	s_waitcnt lgkmcnt(0)
	v_mul_f32_e32 v71, v73, v63
	v_fmac_f32_e32 v71, v72, v62
	v_fmac_f32_e32 v71, v74, v60
	v_fmac_f32_e32 v71, v75, v61
	ds_read_b128 v[72:75], v70 offset:5136
	v_add_f32_e32 v71, 0, v71
	s_waitcnt lgkmcnt(0)
	v_mul_f32_e32 v73, v73, v55
	v_fmac_f32_e32 v73, v72, v54
	v_fmac_f32_e32 v73, v74, v52
	v_fmac_f32_e32 v73, v75, v53
	v_add_f32_e32 v71, v73, v71
	ds_read_b128 v[72:75], v70 offset:6160
	s_waitcnt lgkmcnt(0)
	v_mul_f32_e32 v73, v73, v59
	v_fmac_f32_e32 v73, v72, v58
	v_fmac_f32_e32 v73, v74, v56
	v_fmac_f32_e32 v73, v75, v57
	v_add_f32_e32 v71, v73, v71
	ds_read_b128 v[72:75], v70 offset:7184
	s_waitcnt lgkmcnt(0)
	v_mul_f32_e32 v73, v73, v51
	v_fmac_f32_e32 v73, v72, v50
	v_fmac_f32_e32 v73, v74, v48
	v_fmac_f32_e32 v73, v75, v49
	v_add_f32_e32 v71, v73, v71
	ds_read_b128 v[72:75], v70 offset:8224
	s_waitcnt lgkmcnt(0)
	v_mul_f32_e32 v73, v73, v63
	v_fmac_f32_e32 v73, v72, v62
	v_fmac_f32_e32 v73, v74, v60
	v_fmac_f32_e32 v73, v75, v61
	v_add_f32_e32 v76, 0, v73
	ds_read_b128 v[72:75], v70 offset:9248
	s_waitcnt lgkmcnt(0)
	v_mul_f32_e32 v73, v73, v55
	v_fmac_f32_e32 v73, v72, v54
	v_fmac_f32_e32 v73, v74, v52
	v_fmac_f32_e32 v73, v75, v53
	v_add_f32_e32 v76, v73, v76
	ds_read_b128 v[72:75], v70 offset:10272
	s_waitcnt lgkmcnt(0)
	v_mul_f32_e32 v73, v73, v59
	v_fmac_f32_e32 v73, v72, v58
	v_fmac_f32_e32 v73, v74, v56
	v_fmac_f32_e32 v73, v75, v57
	v_add_f32_e32 v76, v73, v76
	ds_read_b128 v[72:75], v70 offset:11296
	s_waitcnt lgkmcnt(0)
	v_mul_f32_e32 v73, v73, v51
	v_fmac_f32_e32 v73, v72, v50
	v_fmac_f32_e32 v73, v74, v48
	v_fmac_f32_e32 v73, v75, v49
	v_add_f32_e32 v72, v73, v76
	ds_read_b128 v[74:77], v70 offset:12336
	s_waitcnt lgkmcnt(0)
	v_mul_f32_e32 v73, v75, v63
	v_fmac_f32_e32 v73, v74, v62
	v_fmac_f32_e32 v73, v76, v60
	v_fmac_f32_e32 v73, v77, v61
	ds_read_b128 v[74:77], v70 offset:13360
	v_add_f32_e32 v73, 0, v73
	s_waitcnt lgkmcnt(0)
	v_mul_f32_e32 v75, v55, v75
	v_fmac_f32_e32 v75, v54, v74
	v_fmac_f32_e32 v75, v52, v76
	v_fmac_f32_e32 v75, v53, v77
	v_add_f32_e32 v73, v73, v75
	ds_read_b128 v[74:77], v70 offset:14384
	s_waitcnt lgkmcnt(0)
	v_mul_f32_e32 v75, v59, v75
	v_fmac_f32_e32 v75, v58, v74
	v_fmac_f32_e32 v75, v56, v76
	v_fmac_f32_e32 v75, v57, v77
	v_add_f32_e32 v73, v73, v75
	ds_read_b128 v[74:77], v70 offset:15408
	s_waitcnt lgkmcnt(0)
	v_mul_f32_e32 v75, v51, v75
	v_fmac_f32_e32 v75, v50, v74
	v_fmac_f32_e32 v75, v48, v76
	v_fmac_f32_e32 v75, v49, v77
	v_add_f32_e32 v73, v73, v75
	ds_read_b128 v[74:77], v70 offset:16448
	s_waitcnt lgkmcnt(0)
	v_mul_f32_e32 v75, v63, v75
	v_fmac_f32_e32 v75, v62, v74
	v_fmac_f32_e32 v75, v60, v76
	v_fmac_f32_e32 v75, v61, v77
	v_add_f32_e32 v78, 0, v75
	ds_read_b128 v[74:77], v70 offset:17472
	s_waitcnt lgkmcnt(0)
	v_mul_f32_e32 v75, v55, v75
	v_fmac_f32_e32 v75, v54, v74
	v_fmac_f32_e32 v75, v52, v76
	v_fmac_f32_e32 v75, v53, v77
	v_add_f32_e32 v78, v78, v75
	ds_read_b128 v[74:77], v70 offset:18496
	s_waitcnt lgkmcnt(0)
	v_mul_f32_e32 v75, v59, v75
	v_fmac_f32_e32 v75, v58, v74
	v_fmac_f32_e32 v75, v56, v76
	v_fmac_f32_e32 v75, v57, v77
	v_add_f32_e32 v78, v78, v75
	ds_read_b128 v[74:77], v70 offset:19520
	s_waitcnt lgkmcnt(0)
	v_mul_f32_e32 v75, v51, v75
	v_fmac_f32_e32 v75, v50, v74
	v_fmac_f32_e32 v75, v48, v76
	v_fmac_f32_e32 v75, v49, v77
	v_add_f32_e32 v74, v78, v75
	ds_read_b128 v[76:79], v70 offset:20560
	s_waitcnt lgkmcnt(0)
	v_mul_f32_e32 v75, v63, v77
	v_fmac_f32_e32 v75, v62, v76
	v_fmac_f32_e32 v75, v60, v78
	v_fmac_f32_e32 v75, v61, v79
	ds_read_b128 v[76:79], v70 offset:21584
	v_add_f32_e32 v75, 0, v75
	s_waitcnt lgkmcnt(0)
	v_mul_f32_e32 v77, v55, v77
	v_fmac_f32_e32 v77, v54, v76
	v_fmac_f32_e32 v77, v52, v78
	v_fmac_f32_e32 v77, v53, v79
	v_add_f32_e32 v75, v75, v77
	ds_read_b128 v[76:79], v70 offset:22608
	s_waitcnt lgkmcnt(0)
	v_mul_f32_e32 v77, v59, v77
	v_fmac_f32_e32 v77, v58, v76
	v_fmac_f32_e32 v77, v56, v78
	v_fmac_f32_e32 v77, v57, v79
	v_add_f32_e32 v75, v75, v77
	ds_read_b128 v[76:79], v70 offset:23632
	s_waitcnt lgkmcnt(0)
	v_mul_f32_e32 v77, v51, v77
	v_fmac_f32_e32 v77, v50, v76
	v_fmac_f32_e32 v77, v48, v78
	v_fmac_f32_e32 v77, v49, v79
	v_add_f32_e32 v75, v75, v77
	ds_read_b128 v[76:79], v70 offset:24672
	s_waitcnt lgkmcnt(0)
	v_mul_f32_e32 v77, v63, v77
	v_fmac_f32_e32 v77, v62, v76
	v_fmac_f32_e32 v77, v60, v78
	v_fmac_f32_e32 v77, v61, v79
	v_add_f32_e32 v80, 0, v77
	ds_read_b128 v[76:79], v70 offset:25696
	s_waitcnt lgkmcnt(0)
	v_mul_f32_e32 v77, v55, v77
	v_fmac_f32_e32 v77, v54, v76
	v_fmac_f32_e32 v77, v52, v78
	v_fmac_f32_e32 v77, v53, v79
	v_add_f32_e32 v80, v80, v77
	ds_read_b128 v[76:79], v70 offset:26720
	s_waitcnt lgkmcnt(0)
	v_mul_f32_e32 v77, v59, v77
	v_fmac_f32_e32 v77, v58, v76
	v_fmac_f32_e32 v77, v56, v78
	v_fmac_f32_e32 v77, v57, v79
	v_add_f32_e32 v80, v80, v77
	ds_read_b128 v[76:79], v70 offset:27744
	s_waitcnt lgkmcnt(0)
; #define LAS __attribute__((address_space(3)))
; __device__ void phase_ln1_router(const Params& p, int l, LAS unsigned char* lds) {
;     ...
;         float a16[16];
; #pragma unroll
;         for (int e = 0; e < 16; ++e) { float a = 0.f;
; #pragma unroll
;             for (int j = 0; j < 4; ++j) { const f32x4 w = *(const LAS f32x4*)(rw_s + e * RWP + lane * 4 + 256 * j); a += v[j][0] * w[0] + v[j][1] * w[1] + v[j][2] * w[2] + v[j][3] * w[3]; }
;             a16[e] = a; }
	v_mul_f32_e32 v77, v51, v77
	v_fmac_f32_e32 v77, v50, v76
	v_fmac_f32_e32 v77, v48, v78
	v_fmac_f32_e32 v77, v49, v79
	v_add_f32_e32 v76, v80, v77
	ds_read_b128 v[78:81], v70 offset:28784
	s_waitcnt lgkmcnt(0)
	v_mul_f32_e32 v77, v63, v79
	v_fmac_f32_e32 v77, v62, v78
	v_fmac_f32_e32 v77, v60, v80
	v_fmac_f32_e32 v77, v61, v81
	ds_read_b128 v[78:81], v70 offset:29808
	v_add_f32_e32 v77, 0, v77
	s_waitcnt lgkmcnt(0)
	v_mul_f32_e32 v79, v55, v79
	v_fmac_f32_e32 v79, v54, v78
	v_fmac_f32_e32 v79, v52, v80
	v_fmac_f32_e32 v79, v53, v81
	v_add_f32_e32 v77, v77, v79
	ds_read_b128 v[78:81], v70 offset:30832
	s_waitcnt lgkmcnt(0)
	v_mul_f32_e32 v79, v59, v79
	v_fmac_f32_e32 v79, v58, v78
	v_fmac_f32_e32 v79, v56, v80
	v_fmac_f32_e32 v79, v57, v81
	v_add_f32_e32 v77, v77, v79
	ds_read_b128 v[78:81], v70 offset:31856
	s_waitcnt lgkmcnt(0)
	v_mul_f32_e32 v79, v51, v79
	v_fmac_f32_e32 v79, v50, v78
	v_fmac_f32_e32 v79, v48, v80
	v_fmac_f32_e32 v79, v49, v81
	v_add_f32_e32 v77, v77, v79
	ds_read_b128 v[78:81], v70 offset:32896
	s_waitcnt lgkmcnt(0)
	v_mul_f32_e32 v79, v63, v79
	v_fmac_f32_e32 v79, v62, v78
	v_fmac_f32_e32 v79, v60, v80
	v_fmac_f32_e32 v79, v61, v81
	v_add_f32_e32 v82, 0, v79
	ds_read_b128 v[78:81], v70 offset:33920
	s_waitcnt lgkmcnt(0)
	v_mul_f32_e32 v79, v55, v79
	v_fmac_f32_e32 v79, v54, v78
	v_fmac_f32_e32 v79, v52, v80
	v_fmac_f32_e32 v79, v53, v81
	v_add_f32_e32 v82, v82, v79
	ds_read_b128 v[78:81], v70 offset:34944
	s_waitcnt lgkmcnt(0)
	v_mul_f32_e32 v79, v59, v79
	v_fmac_f32_e32 v79, v58, v78
	v_fmac_f32_e32 v79, v56, v80
	v_fmac_f32_e32 v79, v57, v81
	v_add_f32_e32 v82, v82, v79
	ds_read_b128 v[78:81], v70 offset:35968
	s_waitcnt lgkmcnt(0)
	v_mul_f32_e32 v79, v51, v79
	v_fmac_f32_e32 v79, v50, v78
	v_fmac_f32_e32 v79, v48, v80
	v_fmac_f32_e32 v79, v49, v81
	v_add_f32_e32 v78, v82, v79
	ds_read_b128 v[80:83], v70 offset:37008
	s_waitcnt lgkmcnt(0)
	v_mul_f32_e32 v79, v63, v81
	v_fmac_f32_e32 v79, v62, v80
	v_fmac_f32_e32 v79, v60, v82
	v_fmac_f32_e32 v79, v61, v83
	ds_read_b128 v[80:83], v70 offset:38032
	v_add_f32_e32 v79, 0, v79
	s_waitcnt lgkmcnt(0)
	v_mul_f32_e32 v81, v55, v81
	v_fmac_f32_e32 v81, v54, v80
	v_fmac_f32_e32 v81, v52, v82
	v_fmac_f32_e32 v81, v53, v83
	v_add_f32_e32 v79, v79, v81
	ds_read_b128 v[80:83], v70 offset:39056
	s_waitcnt lgkmcnt(0)
	v_mul_f32_e32 v81, v59, v81
	v_fmac_f32_e32 v81, v58, v80
	v_fmac_f32_e32 v81, v56, v82
	v_fmac_f32_e32 v81, v57, v83
	v_add_f32_e32 v79, v79, v81
	ds_read_b128 v[80:83], v70 offset:40080
	s_waitcnt lgkmcnt(0)
	v_mul_f32_e32 v81, v51, v81
	v_fmac_f32_e32 v81, v50, v80
	v_fmac_f32_e32 v81, v48, v82
	v_fmac_f32_e32 v81, v49, v83
	v_add_f32_e32 v79, v79, v81
	ds_read_b128 v[80:83], v70 offset:41120
	s_waitcnt lgkmcnt(0)
	v_mul_f32_e32 v81, v63, v81
	v_fmac_f32_e32 v81, v62, v80
	v_fmac_f32_e32 v81, v60, v82
	v_fmac_f32_e32 v81, v61, v83
	v_add_f32_e32 v84, 0, v81
	ds_read_b128 v[80:83], v70 offset:42144
	s_waitcnt lgkmcnt(0)
	v_mul_f32_e32 v81, v55, v81
	v_fmac_f32_e32 v81, v54, v80
	v_fmac_f32_e32 v81, v52, v82
	v_fmac_f32_e32 v81, v53, v83
	v_add_f32_e32 v84, v84, v81
	ds_read_b128 v[80:83], v70 offset:43168
	s_waitcnt lgkmcnt(0)
	v_mul_f32_e32 v81, v59, v81
	v_fmac_f32_e32 v81, v58, v80
	v_fmac_f32_e32 v81, v56, v82
	v_fmac_f32_e32 v81, v57, v83
	v_add_f32_e32 v84, v84, v81
	ds_read_b128 v[80:83], v70 offset:44192
	s_waitcnt lgkmcnt(0)
	v_mul_f32_e32 v81, v51, v81
	v_fmac_f32_e32 v81, v50, v80
	v_fmac_f32_e32 v81, v48, v82
	v_fmac_f32_e32 v81, v49, v83
	v_add_f32_e32 v80, v84, v81
	ds_read_b128 v[82:85], v70 offset:45232
	s_waitcnt lgkmcnt(0)
	v_mul_f32_e32 v81, v63, v83
	v_fmac_f32_e32 v81, v62, v82
	v_fmac_f32_e32 v81, v60, v84
	v_fmac_f32_e32 v81, v61, v85
	ds_read_b128 v[82:85], v70 offset:46256
	v_add_f32_e32 v81, 0, v81
	s_waitcnt lgkmcnt(0)
	v_mul_f32_e32 v83, v55, v83
	v_fmac_f32_e32 v83, v54, v82
	v_fmac_f32_e32 v83, v52, v84
	v_fmac_f32_e32 v83, v53, v85
	v_add_f32_e32 v81, v81, v83
	ds_read_b128 v[82:85], v70 offset:47280
	s_waitcnt lgkmcnt(0)
	v_mul_f32_e32 v83, v59, v83
	v_fmac_f32_e32 v83, v58, v82
	v_fmac_f32_e32 v83, v56, v84
	v_fmac_f32_e32 v83, v57, v85
	v_add_f32_e32 v81, v81, v83
	ds_read_b128 v[82:85], v70 offset:48304
	s_waitcnt lgkmcnt(0)
	v_mul_f32_e32 v83, v51, v83
	v_fmac_f32_e32 v83, v50, v82
	v_fmac_f32_e32 v83, v48, v84
	v_fmac_f32_e32 v83, v49, v85
	v_add_f32_e32 v81, v81, v83
	ds_read_b128 v[82:85], v70 offset:49344
	s_waitcnt lgkmcnt(0)
	v_mul_f32_e32 v83, v63, v83
	v_fmac_f32_e32 v83, v62, v82
	v_fmac_f32_e32 v83, v60, v84
	v_fmac_f32_e32 v83, v61, v85
	v_add_f32_e32 v86, 0, v83
	ds_read_b128 v[82:85], v70 offset:50368
	s_waitcnt lgkmcnt(0)
	v_mul_f32_e32 v83, v55, v83
	v_fmac_f32_e32 v83, v54, v82
	v_fmac_f32_e32 v83, v52, v84
	v_fmac_f32_e32 v83, v53, v85
	v_add_f32_e32 v86, v86, v83
	ds_read_b128 v[82:85], v70 offset:51392
	s_waitcnt lgkmcnt(0)
	v_mul_f32_e32 v83, v59, v83
	v_fmac_f32_e32 v83, v58, v82
	v_fmac_f32_e32 v83, v56, v84
	v_fmac_f32_e32 v83, v57, v85
	v_add_f32_e32 v86, v86, v83
	ds_read_b128 v[82:85], v70 offset:52416
	s_waitcnt lgkmcnt(0)
	v_mul_f32_e32 v83, v51, v83
	v_fmac_f32_e32 v83, v50, v82
	v_fmac_f32_e32 v83, v48, v84
	v_fmac_f32_e32 v83, v49, v85
	v_add_f32_e32 v82, v86, v83
	ds_read_b128 v[84:87], v70 offset:53456
	s_waitcnt lgkmcnt(0)
	v_mul_f32_e32 v83, v63, v85
	v_fmac_f32_e32 v83, v62, v84
	v_fmac_f32_e32 v83, v60, v86
	v_fmac_f32_e32 v83, v61, v87
	ds_read_b128 v[84:87], v70 offset:54480
	v_add_f32_e32 v83, 0, v83
	s_waitcnt lgkmcnt(0)
	v_mul_f32_e32 v85, v55, v85
	v_fmac_f32_e32 v85, v54, v84
	v_fmac_f32_e32 v85, v52, v86
	v_fmac_f32_e32 v85, v53, v87
	v_add_f32_e32 v83, v83, v85
	ds_read_b128 v[84:87], v70 offset:55504
	s_waitcnt lgkmcnt(0)
; #define LAS __attribute__((address_space(3)))
; __device__ void phase_ln1_router(const Params& p, int l, LAS unsigned char* lds) {
;     ...
;         for (int e = 0; e < 16; ++e) { float a = 0.f;
; #pragma unroll
;             for (int j = 0; j < 4; ++j) { const f32x4 w = *(const LAS f32x4*)(rw_s + e * RWP + lane * 4 + 256 * j); a += v[j][0] * w[0] + v[j][1] * w[1] + v[j][2] * w[2] + v[j][3] * w[3]; }
;             a16[e] = a; }
;         float b8[8], c4[4], d2[2];
;         { const bool hi = (lane & 32) != 0;
; #pragma unroll
;           for (int i = 0; i < 8; ++i) { const float keep = hi ? a16[8 + i] : a16[i], send = hi ? a16[i] : a16[8 + i]; b8[i] = keep + __shfl_xor(send, 32); } }
;         { const bool hi = (lane & 16) != 0;
; #pragma unroll
;           for (int i = 0; i < 4; ++i) { const float keep = hi ? b8[4 + i] : b8[i], send = hi ? b8[i] : b8[4 + i]; c4[i] = keep + __shfl_xor(send, 16); } }
;         { const bool hi = (lane & 8) != 0;
; #pragma unroll
;           for (int i = 0; i < 2; ++i) { const float keep = hi ? c4[2 + i] : c4[i], send = hi ? c4[i] : c4[2 + i]; d2[i] = keep + __shfl_xor(send, 8); } }
;         float lgt; { const bool hi = (lane & 4) != 0; const float keep = hi ? d2[1] : d2[0], send = hi ? d2[0] : d2[1]; lgt = keep + __shfl_xor(send, 4); }
;         lgt += __shfl_xor(lgt, 2); lgt += __shfl_xor(lgt, 1);
;         float mx = lgt;
;         mx = fmaxf(mx, __shfl_xor(mx, 4)); mx = fmaxf(mx, __shfl_xor(mx, 8)); mx = fmaxf(mx, __shfl_xor(mx, 16)); mx = fmaxf(mx, __shfl_xor(mx, 32));
;         const float ex = expf(lgt - mx);
;         float den = ex; den += __shfl_xor(den, 4); den += __shfl_xor(den, 8); den += __shfl_xor(den, 16); den += __shfl_xor(den, 32);
;         const int eidx = ((lane >> 5) & 1) * 8 + ((lane >> 4) & 1) * 4 + ((lane >> 3) & 1) * 2 + ((lane >> 2) & 1);
;         if ((lane & 3) == 0) AFF[(size_t)eidx * SEQ + row] = ex / den;
	v_mul_f32_e32 v85, v59, v85
	v_fmac_f32_e32 v85, v58, v84
	v_fmac_f32_e32 v85, v56, v86
	v_fmac_f32_e32 v85, v57, v87
	v_add_f32_e32 v83, v83, v85
	ds_read_b128 v[84:87], v70 offset:56528
	s_waitcnt lgkmcnt(0)
	v_mul_f32_e32 v85, v51, v85
	v_fmac_f32_e32 v85, v50, v84
	v_fmac_f32_e32 v85, v48, v86
	v_fmac_f32_e32 v85, v49, v87
	v_add_f32_e32 v83, v83, v85
	ds_read_b128 v[84:87], v70 offset:57568
	s_waitcnt lgkmcnt(0)
	v_mul_f32_e32 v85, v63, v85
	v_fmac_f32_e32 v85, v62, v84
	v_fmac_f32_e32 v85, v60, v86
	v_fmac_f32_e32 v85, v61, v87
	v_add_f32_e32 v88, 0, v85
	ds_read_b128 v[84:87], v70 offset:58592
	s_waitcnt lgkmcnt(0)
	v_mul_f32_e32 v85, v55, v85
	v_fmac_f32_e32 v85, v54, v84
	v_fmac_f32_e32 v85, v52, v86
	v_fmac_f32_e32 v85, v53, v87
	v_add_f32_e32 v88, v88, v85
	ds_read_b128 v[84:87], v70 offset:59616
	s_waitcnt lgkmcnt(0)
	v_mul_f32_e32 v85, v59, v85
	v_fmac_f32_e32 v85, v58, v84
	v_fmac_f32_e32 v85, v56, v86
	v_fmac_f32_e32 v85, v57, v87
	v_add_f32_e32 v88, v88, v85
	ds_read_b128 v[84:87], v70 offset:60640
	s_waitcnt lgkmcnt(0)
	v_mul_f32_e32 v85, v51, v85
	v_fmac_f32_e32 v85, v50, v84
	v_fmac_f32_e32 v85, v48, v86
	v_fmac_f32_e32 v85, v49, v87
	v_add_f32_e32 v88, v88, v85
	ds_read_b128 v[84:87], v70 offset:61680
	s_waitcnt lgkmcnt(0)
	v_mul_f32_e32 v63, v63, v85
	v_fmac_f32_e32 v63, v62, v84
	v_fmac_f32_e32 v63, v60, v86
	v_fmac_f32_e32 v63, v61, v87
	v_add_f32_e32 v84, 0, v63
	ds_read_b128 v[60:63], v70 offset:62704
	s_waitcnt lgkmcnt(0)
	v_mul_f32_e32 v55, v55, v61
	v_fmac_f32_e32 v55, v54, v60
	v_fmac_f32_e32 v55, v52, v62
	v_fmac_f32_e32 v55, v53, v63
	v_add_f32_e32 v60, v84, v55
	ds_read_b128 v[52:55], v70 offset:63728
	s_waitcnt lgkmcnt(0)
	v_mul_f32_e32 v53, v59, v53
	v_fmac_f32_e32 v53, v58, v52
	v_fmac_f32_e32 v53, v56, v54
	v_fmac_f32_e32 v53, v57, v55
	v_add_f32_e32 v56, v60, v53
	ds_read_b128 v[52:55], v70 offset:64752
	s_waitcnt lgkmcnt(0)
	v_mul_f32_e32 v51, v51, v53
	v_fmac_f32_e32 v51, v50, v52
	v_fmac_f32_e32 v51, v48, v54
	v_fmac_f32_e32 v51, v49, v55
	v_cndmask_b32_e64 v49, v78, v33, s[4:5]
	v_cndmask_b32_e64 v33, v33, v78, s[4:5]
	ds_bpermute_b32 v33, v64, v33
	v_cndmask_b32_e64 v50, v71, v79, s[4:5]
	v_add_f32_e32 v48, v56, v51
	ds_bpermute_b32 v50, v64, v50
	v_cndmask_b32_e64 v51, v72, v80, s[4:5]
	ds_bpermute_b32 v51, v64, v51
	v_cndmask_b32_e64 v52, v73, v81, s[4:5]
	ds_bpermute_b32 v52, v64, v52
	v_cndmask_b32_e64 v53, v74, v82, s[4:5]
	ds_bpermute_b32 v53, v64, v53
	v_cndmask_b32_e64 v54, v75, v83, s[4:5]
	s_waitcnt lgkmcnt(4)
	v_add_f32_e32 v33, v49, v33
	v_cndmask_b32_e64 v49, v79, v71, s[4:5]
	ds_bpermute_b32 v54, v64, v54
	v_cndmask_b32_e64 v55, v76, v88, s[4:5]
	s_waitcnt lgkmcnt(4)
	v_add_f32_e32 v49, v49, v50
	v_cndmask_b32_e64 v50, v80, v72, s[4:5]
	ds_bpermute_b32 v55, v64, v55
	s_waitcnt lgkmcnt(4)
	v_add_f32_e32 v50, v50, v51
	v_cndmask_b32_e64 v51, v81, v73, s[4:5]
	s_waitcnt lgkmcnt(3)
	v_add_f32_e32 v51, v51, v52
	v_cndmask_b32_e64 v52, v82, v74, s[4:5]
	s_waitcnt lgkmcnt(2)
	v_add_f32_e32 v52, v52, v53
	v_cndmask_b32_e64 v53, v83, v75, s[4:5]
	s_waitcnt lgkmcnt(1)
	v_add_f32_e32 v53, v53, v54
	v_cndmask_b32_e64 v54, v88, v76, s[4:5]
	s_waitcnt lgkmcnt(0)
	v_add_f32_e32 v54, v54, v55
	v_cndmask_b32_e64 v55, v48, v77, s[4:5]
	v_cndmask_b32_e64 v48, v77, v48, s[4:5]
	ds_bpermute_b32 v48, v64, v48
	s_waitcnt lgkmcnt(0)
	v_add_f32_e32 v48, v55, v48
	v_cndmask_b32_e64 v55, v52, v33, s[6:7]
	v_cndmask_b32_e64 v33, v33, v52, s[6:7]
	v_cndmask_b32_e64 v52, v53, v49, s[6:7]
	v_cndmask_b32_e64 v49, v49, v53, s[6:7]
	ds_bpermute_b32 v49, v65, v49
	ds_bpermute_b32 v33, v65, v33
	s_waitcnt lgkmcnt(1)
	v_add_f32_e32 v49, v52, v49
	v_cndmask_b32_e64 v52, v54, v50, s[6:7]
	v_cndmask_b32_e64 v50, v50, v54, s[6:7]
	ds_bpermute_b32 v50, v65, v50
	s_waitcnt lgkmcnt(1)
	v_add_f32_e32 v33, v55, v33
	s_waitcnt lgkmcnt(0)
	v_add_f32_e32 v50, v52, v50
	v_cndmask_b32_e64 v52, v48, v51, s[6:7]
	v_cndmask_b32_e64 v48, v51, v48, s[6:7]
	ds_bpermute_b32 v48, v65, v48
	v_cndmask_b32_e64 v51, v50, v33, s[8:9]
	v_cndmask_b32_e64 v33, v33, v50, s[8:9]
	ds_bpermute_b32 v33, v66, v33
	s_waitcnt lgkmcnt(1)
	v_add_f32_e32 v48, v52, v48
	v_cndmask_b32_e64 v50, v48, v49, s[8:9]
	v_cndmask_b32_e64 v48, v49, v48, s[8:9]
	ds_bpermute_b32 v48, v66, v48
	s_waitcnt lgkmcnt(1)
	v_add_f32_e32 v33, v51, v33
	s_waitcnt lgkmcnt(0)
	v_add_f32_e32 v48, v50, v48
	v_cndmask_b32_e64 v49, v48, v33, s[10:11]
	v_cndmask_b32_e64 v33, v33, v48, s[10:11]
	ds_bpermute_b32 v33, v67, v33
	s_waitcnt lgkmcnt(0)
	v_add_f32_e32 v33, v49, v33
	s_waitcnt lgkmcnt(0)
	s_nop 1
	v_add_f32_dpp v33, v33, v33 quad_perm:[2,3,0,1] row_mask:0xf bank_mask:0xf
	s_waitcnt lgkmcnt(0)
	s_nop 1
	v_add_f32_dpp v33, v33, v33 quad_perm:[1,0,3,2] row_mask:0xf bank_mask:0xf
	ds_bpermute_b32 v48, v67, v33
	s_waitcnt lgkmcnt(0)
	v_max_f32_e32 v48, v48, v48
	v_max_f32_e32 v48, v33, v48
	s_waitcnt lgkmcnt(0)
	s_nop 1
	v_max_f32_dpp v48, v48, v48 row_ror:8 row_mask:0xf bank_mask:0xf
	v_mov_b32_e32 v49, v48
	s_waitcnt lgkmcnt(0)
	s_nop 1
	v_permlane16_swap_b32_e32 v49, v48
	v_max_f32_e32 v48, v48, v49
	v_mov_b32_e32 v49, v48
	s_waitcnt lgkmcnt(0)
	s_nop 1
	v_permlane32_swap_b32_e32 v49, v48
	v_max_f32_e32 v48, v48, v49
	v_sub_f32_e32 v33, v33, v48
	v_mul_f32_e32 v48, 0x3fb8aa3b, v33
	v_fma_f32 v49, v33, s20, -v48
	v_rndne_f32_e32 v50, v48
	v_fmac_f32_e32 v49, 0x32a5705f, v33
	v_sub_f32_e32 v48, v48, v50
	v_add_f32_e32 v48, v48, v49
	v_exp_f32_e32 v48, v48
	v_cvt_i32_f32_e32 v49, v50
	s_mov_b32 s20, 0xc2ce8ed0
	v_cmp_ngt_f32_e32 vcc, s20, v33
	s_mov_b32 s20, 0x42b17218
	v_ldexp_f32 v48, v48, v49
	v_cndmask_b32_e32 v48, 0, v48, vcc
	v_cmp_nlt_f32_e32 vcc, s20, v33
	v_mov_b32_e32 v33, 0x7f800000
	s_nop 0
	v_cndmask_b32_e32 v33, v33, v48, vcc
	ds_bpermute_b32 v48, v67, v33
	s_waitcnt lgkmcnt(0)
	v_add_f32_e32 v48, v33, v48
	s_waitcnt lgkmcnt(0)
	s_nop 1
	v_add_f32_dpp v48, v48, v48 row_ror:8 row_mask:0xf bank_mask:0xf
	v_mov_b32_e32 v49, v48
	s_waitcnt lgkmcnt(0)
	s_nop 1
	v_permlane16_swap_b32_e32 v49, v48
	v_add_f32_e32 v48, v48, v49
	ds_bpermute_b32 v49, v64, v48
	s_and_saveexec_b64 s[20:21], s[12:13]
	s_cbranch_execz .LBB0_313
	s_waitcnt lgkmcnt(0)
	v_add_f32_e32 v48, v48, v49
	v_div_scale_f32 v49, s[22:23], v48, v48, v33
	v_rcp_f32_e32 v50, v49
	v_div_scale_f32 v51, vcc, v33, v48, v33
	v_fma_f32 v52, -v49, v50, 1.0
	v_fmac_f32_e32 v50, v52, v50
	v_mul_f32_e32 v52, v51, v50
	v_fma_f32 v53, -v49, v52, v51
	v_fmac_f32_e32 v52, v53, v50
	v_fma_f32 v49, -v49, v52, v51
	v_div_fmas_f32 v49, v49, v50, v52
	v_div_fixup_f32 v33, v49, v48, v33
	v_lshl_add_u64 v[48:49], s[86:87], 0, v[38:39]
	global_store_dword v[48:49], v33, off
	s_branch .LBB0_313

; #define LAS __attribute__((address_space(3)))
; __device__ __forceinline__ unsigned cvt_pk_bf16_mfma(float lo, float hi) { const f32x2 v = {lo, hi}; return __builtin_bit_cast(unsigned, __builtin_convertvector(v, bf16v2_t)); }
; template <bool OUT>
; __device__ __forceinline__ void gla_chunks(const Params& p, int l, const bf16_t* proj, LAS unsigned char* lds, int seg, int h, int dir, f32x4 (&Sacc)[4], float* outbuf, float& alog) {
;     ...
;         bf16x8 bv[2];
; #pragma unroll
;         for (int ks = 0; ks < 2; ++ks) bv[ks] = *(const LAS bf16x8*)(VT + (16 * wv + fr) * GP + 32 * ks + 8 * g);
;         if (OUT) {
;             bf16x8 bs[2];
; #pragma unroll
;             for (int m = 0; m < 2; ++m) { u32x4 sw; sw.x = cvt_pk_bf16_mfma(Sacc[2 * m][0], Sacc[2 * m][1]); sw.y = cvt_pk_bf16_mfma(Sacc[2 * m][2], Sacc[2 * m][3]); sw.z = cvt_pk_bf16_mfma(Sacc[2 * m + 1][0], Sacc[2 * m + 1][1]); sw.w = cvt_pk_bf16_mfma(Sacc[2 * m + 1][2], Sacc[2 * m + 1][3]); bs[m] = __builtin_bit_cast(bf16x8, sw); }
; #pragma unroll
;             for (int it = 0; it < 4; ++it) { f32x4 o = {0.f, 0.f, 0.f, 0.f};
; #pragma unroll
;                 for (int ks = 0; ks < 2; ++ks) { const bf16x8 pf = *(const LAS bf16x8*)(PP + (it * 16 + fr) * GP + 32 * ks + 8 * g); o = __builtin_amdgcn_mfma_f32_16x16x32_bf16(pf, bv[ks], o, 0, 0, 0); }
; #pragma unroll
;                 for (int m = 0; m < 2; ++m) { const LAS bf16_t* qp = QT + (it * 16 + fr) * GP + 32 * m + 4 * g; const u32x2 lo = *(const LAS u32x2*)qp, hi = *(const LAS u32x2*)(qp + 16);
;                     u32x4 qw; qw.x = lo.x; qw.y = lo.y; qw.z = hi.x; qw.w = hi.y; o = __builtin_amdgcn_mfma_f32_16x16x32_bf16(__builtin_bit_cast(bf16x8, qw), bs[m], o, 0, 0, 0); }
; #pragma unroll
;                 for (int r = 0; r < 4; ++r) { const int i = it * 16 + 4 * g + r, t = dir ? t0 + 63 - i : t0 + i; outbuf[(size_t)t * 512 + h * 128 + 16 * wv + fr] = o[r]; } }
;         }
; #pragma unroll
;         for (int dt = 0; dt < 4; ++dt) { const f32x4 eb = *(const LAS f32x4*)(EBL + dt * 16 + 4 * g); f32x4 a = Sacc[dt] * eb;
; #pragma unroll
;             for (int ks = 0; ks < 2; ++ks) { const bf16x8 kf = *(const LAS bf16x8*)(KH + (dt * 16 + fr) * GP + 32 * ks + 8 * g); a = __builtin_amdgcn_mfma_f32_16x16x32_bf16(kf, bv[ks], a, 0, 0, 0); }
;             Sacc[dt] = a; }
.LBB0_435:
	v_cvt_pk_bf16_f32 v16, v22, v16
	v_cvt_pk_bf16_f32 v17, v17, v18
	s_nop 0
	v_add_u32_e32 v18, v111, v118
	ds_write_b64 v18, v[16:17] offset:46080
	s_waitcnt lgkmcnt(0)
	s_barrier
	ds_read_b128 v[20:23], v135 offset:27648
	ds_read_b128 v[16:19], v135 offset:27712
	ds_read_b128 v[156:159], v136 offset:46080
	ds_read_b128 v[160:163], v136 offset:46144
	ds_read2_b64 v[190:193], v137 offset1:4
	ds_read2_b64 v[194:197], v137 offset0:8 offset1:12
	ds_read_b128 v[164:167], v136 offset:48384
	ds_read_b128 v[168:171], v136 offset:48448
	v_add_u32_e32 v40, 0x800, v137
	ds_read2_b64 v[198:201], v40 offset0:32 offset1:36
	ds_read2_b64 v[202:205], v40 offset0:40 offset1:44
	ds_read_b128 v[172:175], v136 offset:50688
	ds_read_b128 v[176:179], v136 offset:50752
	ds_read_b128 v[180:183], v136 offset:52992
	ds_read_b128 v[184:187], v136 offset:53056
	v_cvt_pk_bf16_f32 v28, v8, v9
	v_cvt_pk_bf16_f32 v29, v10, v11
	v_cvt_pk_bf16_f32 v30, v0, v1
	v_cvt_pk_bf16_f32 v31, v2, v3
	v_cvt_pk_bf16_f32 v24, v4, v5
	v_cvt_pk_bf16_f32 v25, v6, v7
	v_cvt_pk_bf16_f32 v26, v12, v13
	v_cvt_pk_bf16_f32 v27, v14, v15
	s_waitcnt lgkmcnt(11)
	v_mfma_f32_16x16x32_bf16 v[32:35], v[156:159], v[20:23], 0
	s_waitcnt lgkmcnt(10)
	v_mfma_f32_16x16x32_bf16 v[32:35], v[160:163], v[16:19], v[32:35]
	s_waitcnt lgkmcnt(9)
	v_mfma_f32_16x16x32_bf16 v[32:35], v[190:193], v[28:31], v[32:35]
	s_waitcnt lgkmcnt(8)
	v_mfma_f32_16x16x32_bf16 v[32:35], v[194:197], v[24:27], v[32:35]
	v_add_u32_e32 v40, 0x1000, v137
	ds_read2_b64 v[222:225], v40 offset0:64 offset1:68
	ds_read2_b64 v[226:229], v40 offset0:72 offset1:76
	v_add_u32_e32 v40, 0x1800, v137
	ds_read2_b64 v[230:233], v40 offset0:96 offset1:100
	ds_read2_b64 v[234:237], v40 offset0:104 offset1:108
	s_waitcnt lgkmcnt(11)
	v_mfma_f32_16x16x32_bf16 v[36:39], v[164:167], v[20:23], 0
	s_waitcnt lgkmcnt(10)
	v_mfma_f32_16x16x32_bf16 v[36:39], v[168:171], v[16:19], v[36:39]
	s_waitcnt lgkmcnt(9)
	v_mfma_f32_16x16x32_bf16 v[36:39], v[198:201], v[28:31], v[36:39]
	s_waitcnt lgkmcnt(8)
	v_mfma_f32_16x16x32_bf16 v[36:39], v[202:205], v[24:27], v[36:39]
	v_sub_u32_e32 v238, s53, v85
	v_or_b32_e32 v239, s52, v85
	v_cndmask_b32_e64 v238, v238, v239, s[42:43]
	v_ashrrev_i32_e32 v239, 31, v238
	v_lshlrev_b64 v[238:239], 11, v[238:239]
	v_lshl_add_u64 v[238:239], v[86:87], 0, v[238:239]
	global_store_dword v[238:239], v32, off
	v_sub_u32_e32 v240, s53, v119
	v_or_b32_e32 v241, s52, v119
	v_cndmask_b32_e64 v240, v240, v241, s[42:43]
	v_ashrrev_i32_e32 v241, 31, v240
	v_lshlrev_b64 v[240:241], 11, v[240:241]
	v_lshl_add_u64 v[240:241], v[86:87], 0, v[240:241]
	global_store_dword v[240:241], v33, off
	v_sub_u32_e32 v238, s53, v120
	v_or_b32_e32 v239, s52, v120
	v_cndmask_b32_e64 v238, v238, v239, s[42:43]
	v_ashrrev_i32_e32 v239, 31, v238
	v_lshlrev_b64 v[238:239], 11, v[238:239]
	v_lshl_add_u64 v[238:239], v[86:87], 0, v[238:239]
	global_store_dword v[238:239], v34, off
	v_sub_u32_e32 v240, s53, v121
	v_or_b32_e32 v241, s52, v121
	v_cndmask_b32_e64 v240, v240, v241, s[42:43]
	v_ashrrev_i32_e32 v241, 31, v240
	v_lshlrev_b64 v[240:241], 11, v[240:241]
	v_lshl_add_u64 v[240:241], v[86:87], 0, v[240:241]
	global_store_dword v[240:241], v35, off
	s_waitcnt lgkmcnt(7)
	v_mfma_f32_16x16x32_bf16 v[32:35], v[172:175], v[20:23], 0
	s_waitcnt lgkmcnt(6)
	v_mfma_f32_16x16x32_bf16 v[32:35], v[176:179], v[16:19], v[32:35]
	s_waitcnt lgkmcnt(3)
	v_mfma_f32_16x16x32_bf16 v[32:35], v[222:225], v[28:31], v[32:35]
	s_waitcnt lgkmcnt(2)
	v_mfma_f32_16x16x32_bf16 v[32:35], v[226:229], v[24:27], v[32:35]
	v_sub_u32_e32 v238, s53, v122
	v_or_b32_e32 v239, s52, v122
	v_cndmask_b32_e64 v238, v238, v239, s[42:43]
	v_ashrrev_i32_e32 v239, 31, v238
	v_lshlrev_b64 v[238:239], 11, v[238:239]
	v_lshl_add_u64 v[238:239], v[86:87], 0, v[238:239]
	global_store_dword v[238:239], v36, off
	v_sub_u32_e32 v240, s53, v123
	v_or_b32_e32 v241, s52, v123
	v_cndmask_b32_e64 v240, v240, v241, s[42:43]
	v_ashrrev_i32_e32 v241, 31, v240
	v_lshlrev_b64 v[240:241], 11, v[240:241]
	v_lshl_add_u64 v[240:241], v[86:87], 0, v[240:241]
	global_store_dword v[240:241], v37, off
	v_sub_u32_e32 v238, s53, v124
	v_or_b32_e32 v239, s52, v124
	v_cndmask_b32_e64 v238, v238, v239, s[42:43]
	v_ashrrev_i32_e32 v239, 31, v238
	v_lshlrev_b64 v[238:239], 11, v[238:239]
	v_lshl_add_u64 v[238:239], v[86:87], 0, v[238:239]
	global_store_dword v[238:239], v38, off
	v_sub_u32_e32 v240, s53, v125
	v_or_b32_e32 v241, s52, v125
	v_cndmask_b32_e64 v240, v240, v241, s[42:43]
	v_ashrrev_i32_e32 v241, 31, v240
	v_lshlrev_b64 v[240:241], 11, v[240:241]
	v_lshl_add_u64 v[240:241], v[86:87], 0, v[240:241]
	global_store_dword v[240:241], v39, off
	ds_read_b128 v[156:159], v82 offset:55296
	ds_read_b128 v[160:163], v82 offset:55360
	ds_read_b128 v[164:167], v82 offset:55424
	ds_read_b128 v[168:171], v82 offset:55488
	ds_read_b128 v[190:193], v136 offset:18432
	ds_read_b128 v[194:197], v136 offset:18496
	ds_read_b128 v[198:201], v136 offset:20736
	ds_read_b128 v[202:205], v136 offset:20800
	v_mfma_f32_16x16x32_bf16 v[36:39], v[180:183], v[20:23], 0
	v_mfma_f32_16x16x32_bf16 v[36:39], v[184:187], v[16:19], v[36:39]
	s_waitcnt lgkmcnt(9)
; #define LAS __attribute__((address_space(3)))
; template <bool OUT>
; __device__ __forceinline__ void gla_chunks(const Params& p, int l, const bf16_t* proj, LAS unsigned char* lds, int seg, int h, int dir, f32x4 (&Sacc)[4], float* outbuf, float& alog) {
;     ...
; #pragma unroll
;                 for (int m = 0; m < 2; ++m) { const LAS bf16_t* qp = QT + (it * 16 + fr) * GP + 32 * m + 4 * g; const u32x2 lo = *(const LAS u32x2*)qp, hi = *(const LAS u32x2*)(qp + 16);
;                     u32x4 qw; qw.x = lo.x; qw.y = lo.y; qw.z = hi.x; qw.w = hi.y; o = __builtin_amdgcn_mfma_f32_16x16x32_bf16(__builtin_bit_cast(bf16x8, qw), bs[m], o, 0, 0, 0); }
; #pragma unroll
;                 for (int r = 0; r < 4; ++r) { const int i = it * 16 + 4 * g + r, t = dir ? t0 + 63 - i : t0 + i; outbuf[(size_t)t * 512 + h * 128 + 16 * wv + fr] = o[r]; } }
;         }
; #pragma unroll
;         for (int dt = 0; dt < 4; ++dt) { const f32x4 eb = *(const LAS f32x4*)(EBL + dt * 16 + 4 * g); f32x4 a = Sacc[dt] * eb;
; #pragma unroll
;             for (int ks = 0; ks < 2; ++ks) { const bf16x8 kf = *(const LAS bf16x8*)(KH + (dt * 16 + fr) * GP + 32 * ks + 8 * g); a = __builtin_amdgcn_mfma_f32_16x16x32_bf16(kf, bv[ks], a, 0, 0, 0); }
;             Sacc[dt] = a; }
;         __syncthreads();
;     }
	v_mfma_f32_16x16x32_bf16 v[36:39], v[230:233], v[28:31], v[36:39]
	s_waitcnt lgkmcnt(8)
	v_mfma_f32_16x16x32_bf16 v[36:39], v[234:237], v[24:27], v[36:39]
	ds_read_b128 v[172:175], v136 offset:23040
	ds_read_b128 v[176:179], v136 offset:23104
	ds_read_b128 v[180:183], v136 offset:25344
	ds_read_b128 v[184:187], v136 offset:25408
	v_sub_u32_e32 v238, s53, v126
	v_or_b32_e32 v239, s52, v126
	v_cndmask_b32_e64 v238, v238, v239, s[42:43]
	v_ashrrev_i32_e32 v239, 31, v238
	v_lshlrev_b64 v[238:239], 11, v[238:239]
	v_lshl_add_u64 v[238:239], v[86:87], 0, v[238:239]
	global_store_dword v[238:239], v32, off
	v_sub_u32_e32 v240, s53, v127
	v_or_b32_e32 v241, s52, v127
	v_cndmask_b32_e64 v240, v240, v241, s[42:43]
	v_ashrrev_i32_e32 v241, 31, v240
	v_lshlrev_b64 v[240:241], 11, v[240:241]
	v_lshl_add_u64 v[240:241], v[86:87], 0, v[240:241]
	global_store_dword v[240:241], v33, off
	v_sub_u32_e32 v238, s53, v128
	v_or_b32_e32 v239, s52, v128
	v_cndmask_b32_e64 v238, v238, v239, s[42:43]
	v_ashrrev_i32_e32 v239, 31, v238
	v_lshlrev_b64 v[238:239], 11, v[238:239]
	v_lshl_add_u64 v[238:239], v[86:87], 0, v[238:239]
	global_store_dword v[238:239], v34, off
	v_sub_u32_e32 v240, s53, v129
	v_or_b32_e32 v241, s52, v129
	v_cndmask_b32_e64 v240, v240, v241, s[42:43]
	v_ashrrev_i32_e32 v241, 31, v240
	v_lshlrev_b64 v[240:241], 11, v[240:241]
	v_lshl_add_u64 v[240:241], v[86:87], 0, v[240:241]
	global_store_dword v[240:241], v35, off
	s_waitcnt lgkmcnt(8)
	v_pk_mul_f32 v[8:9], v[8:9], v[156:157]
	v_pk_mul_f32 v[10:11], v[10:11], v[158:159]
	v_pk_mul_f32 v[0:1], v[0:1], v[160:161]
	v_pk_mul_f32 v[2:3], v[2:3], v[162:163]
	v_pk_mul_f32 v[4:5], v[4:5], v[164:165]
	v_pk_mul_f32 v[6:7], v[6:7], v[166:167]
	v_pk_mul_f32 v[12:13], v[12:13], v[168:169]
	v_pk_mul_f32 v[14:15], v[14:15], v[170:171]
	v_sub_u32_e32 v238, s53, v130
	v_or_b32_e32 v239, s52, v130
	v_cndmask_b32_e64 v238, v238, v239, s[42:43]
	v_ashrrev_i32_e32 v239, 31, v238
	v_lshlrev_b64 v[238:239], 11, v[238:239]
	v_lshl_add_u64 v[238:239], v[86:87], 0, v[238:239]
	global_store_dword v[238:239], v36, off
	v_sub_u32_e32 v240, s53, v131
	v_or_b32_e32 v241, s52, v131
	v_cndmask_b32_e64 v240, v240, v241, s[42:43]
	v_ashrrev_i32_e32 v241, 31, v240
	v_lshlrev_b64 v[240:241], 11, v[240:241]
	v_lshl_add_u64 v[240:241], v[86:87], 0, v[240:241]
	global_store_dword v[240:241], v37, off
	v_sub_u32_e32 v238, s53, v132
	v_or_b32_e32 v239, s52, v132
	v_cndmask_b32_e64 v238, v238, v239, s[42:43]
	v_ashrrev_i32_e32 v239, 31, v238
	v_lshlrev_b64 v[238:239], 11, v[238:239]
	v_lshl_add_u64 v[238:239], v[86:87], 0, v[238:239]
	global_store_dword v[238:239], v38, off
	v_sub_u32_e32 v240, s53, v133
	v_or_b32_e32 v241, s52, v133
	v_cndmask_b32_e64 v240, v240, v241, s[42:43]
	v_ashrrev_i32_e32 v241, 31, v240
	v_lshlrev_b64 v[240:241], 11, v[240:241]
	v_lshl_add_u64 v[240:241], v[86:87], 0, v[240:241]
	global_store_dword v[240:241], v39, off
	s_waitcnt lgkmcnt(7)
	v_mfma_f32_16x16x32_bf16 v[8:11], v[190:193], v[20:23], v[8:11]
	s_waitcnt lgkmcnt(6)
	v_mfma_f32_16x16x32_bf16 v[8:11], v[194:197], v[16:19], v[8:11]
	s_waitcnt lgkmcnt(5)
	v_mfma_f32_16x16x32_bf16 v[0:3], v[198:201], v[20:23], v[0:3]
	s_waitcnt lgkmcnt(4)
	v_mfma_f32_16x16x32_bf16 v[0:3], v[202:205], v[16:19], v[0:3]
	s_waitcnt lgkmcnt(3)
	v_mfma_f32_16x16x32_bf16 v[4:7], v[172:175], v[20:23], v[4:7]
	s_waitcnt lgkmcnt(2)
	v_mfma_f32_16x16x32_bf16 v[4:7], v[176:179], v[16:19], v[4:7]
	s_waitcnt lgkmcnt(1)
	v_mfma_f32_16x16x32_bf16 v[12:15], v[180:183], v[20:23], v[12:15]
	s_waitcnt lgkmcnt(0)
	v_mfma_f32_16x16x32_bf16 v[12:15], v[184:187], v[16:19], v[12:15]
	s_add_i32 s51, s51, 1
	s_add_i32 s64, s64, -1
	s_cmp_lg_u32 s51, 4
	s_waitcnt lgkmcnt(0)
	s_barrier
	s_cbranch_scc0 .LBB0_433

; __device__ __forceinline__ unsigned cvt_pk_bf16(float lo, float hi) { unsigned r; asm("v_cvt_pk_bf16_f32 %0, %1, %2" : "=v"(r) : "v"(lo), "v"(hi)); return r; }
; __device__ __forceinline__ float bf_lo(unsigned w) { return __uint_as_float(w << 16); }
; __device__ __forceinline__ float bf_hi(unsigned w) { return __uint_as_float(w & 0xffff0000u); }
; __device__ __forceinline__ float wave_sum(float v) {
; #pragma unroll
;     for (int o = 32; o >= 1; o >>= 1) v += __shfl_xor(v, o);
;     return v;
; __device__ void gla_pass2(const Params& p, int l, const bf16_t* proj, bf16_t* ycat, LAS unsigned char* lds) {
;     ...
;         for (int j0 = 0; j0 < 32; j0 += 8) {
;             f32x2 of[8], ob[8]; unsigned rw[8];
; #pragma unroll
;             for (int j = 0; j < 8; ++j) { const int t = seg * SEGLEN + wv * 32 + j0 + j; const size_t oo = (size_t)t * 512 + h * 128 + lane * 2;
;                 of[j] = *(const f32x2*)(OF + oo); ob[j] = *(const f32x2*)(OB + oo); rw[j] = *(const unsigned*)(proj + (size_t)t * NP + GR + h * 128 + lane * 2); }
; #pragma unroll
;             for (int j = 0; j < 8; ++j) { const int t = seg * SEGLEN + wv * 32 + j0 + j;
;                 const float o0 = of[j][0] + ob[j][0], o1 = of[j][1] + ob[j][1];
;                 const float ss = wave_sum(o0 * o0 + o1 * o1);
;                 const float rs = rsqrtf(ss * (1.0f / 128.0f) + 1e-6f);
;                 const float r0 = bf_lo(rw[j]), r1 = bf_hi(rw[j]);
;                 const float y0 = o0 * rs * gg[0] * (r0 / (1.0f + __expf(-r0))), y1 = o1 * rs * gg[1] * (r1 / (1.0f + __expf(-r1)));
;                 *(unsigned*)(ycat + (size_t)2 * SEQ * 512 + (size_t)t * 512 + h * 128 + lane * 2) = cvt_pk_bf16(y0, y1); } }
.LBB0_443:
	v_lshl_add_u64 v[10:11], s[86:87], 0, v[2:3]
	v_add_co_u32_e32 v12, vcc, 0x35861000, v10
	v_lshl_add_u64 v[56:57], s[86:87], 0, v[4:5]
	s_nop 0
	v_addc_co_u32_e32 v13, vcc, 0, v11, vcc
	v_add_co_u32_e32 v10, vcc, 0x37861000, v10
	global_load_dwordx2 v[38:39], v[12:13], off
	s_nop 0
	v_addc_co_u32_e32 v11, vcc, 0, v11, vcc
	global_load_dwordx2 v[54:55], v[10:11], off
	v_add_co_u32_e32 v10, vcc, 0x20604000, v56
	s_mov_b32 s5, 0x35861000
	s_nop 0
	v_addc_co_u32_e32 v11, vcc, 0, v57, vcc
	global_load_dword v53, v[10:11], off offset:512
	v_lshl_add_u64 v[10:11], s[86:87], 0, v[6:7]
	v_add_co_u32_e32 v12, vcc, s5, v10
	s_mov_b32 s5, 0x37861000
	s_nop 0
	v_addc_co_u32_e32 v13, vcc, 0, v11, vcc
	global_load_dwordx2 v[34:35], v[12:13], off offset:2048
	v_add_co_u32_e32 v12, vcc, s5, v10
	s_mov_b32 s5, 0x20607000
	s_nop 0
	v_addc_co_u32_e32 v13, vcc, 0, v11, vcc
	global_load_dwordx2 v[36:37], v[12:13], off offset:2048
	v_add_co_u32_e32 v12, vcc, s5, v56
	s_mov_b32 s5, 0x35862000
	s_nop 0
	v_addc_co_u32_e32 v13, vcc, 0, v57, vcc
	global_load_dword v52, v[12:13], off offset:2560
	v_add_co_u32_e32 v12, vcc, s5, v10
	s_mov_b32 s5, 0x35863000
	s_nop 0
	v_addc_co_u32_e32 v13, vcc, 0, v11, vcc
	v_add_co_u32_e32 v14, vcc, s5, v10
	s_mov_b32 s5, 0x37862000
	s_nop 0
	v_addc_co_u32_e32 v15, vcc, 0, v11, vcc
	v_add_co_u32_e32 v16, vcc, s5, v10
	s_mov_b32 s5, 0x37863000
	s_nop 0
	v_addc_co_u32_e32 v17, vcc, 0, v11, vcc
	v_add_co_u32_e32 v20, vcc, s5, v10
	global_load_dwordx2 v[30:31], v[14:15], off offset:-4096
	s_nop 0
	v_addc_co_u32_e32 v21, vcc, 0, v11, vcc
	global_load_dwordx2 v[32:33], v[20:21], off offset:-4096
	s_mov_b32 s5, 0x2060b000
	v_add_co_u32_e32 v18, vcc, s5, v56
	s_mov_b32 s5, 0x2060e000
	s_nop 0
	v_addc_co_u32_e32 v19, vcc, 0, v57, vcc
	global_load_dword v51, v[18:19], off offset:512
	global_load_dwordx2 v[26:27], v[12:13], off offset:2048
	global_load_dwordx2 v[28:29], v[16:17], off offset:2048
	v_add_co_u32_e32 v12, vcc, s5, v56
	s_mov_b32 s5, 0x20612000
	s_nop 0
	v_addc_co_u32_e32 v13, vcc, 0, v57, vcc
	global_load_dword v50, v[12:13], off offset:2560
	global_load_dwordx2 v[22:23], v[14:15], off
	global_load_dwordx2 v[24:25], v[20:21], off
	v_add_co_u32_e32 v12, vcc, s5, v56
	s_mov_b32 s5, 0x20615000
	s_nop 0
	v_addc_co_u32_e32 v13, vcc, 0, v57, vcc
	global_load_dword v49, v[12:13], off offset:512
	global_load_dwordx2 v[18:19], v[14:15], off offset:2048
	s_nop 0
	global_load_dwordx2 v[20:21], v[20:21], off offset:2048
	v_add_co_u32_e32 v12, vcc, s5, v56
	s_mov_b32 s5, 0x35864000
	s_nop 0
	v_addc_co_u32_e32 v13, vcc, 0, v57, vcc
	global_load_dword v48, v[12:13], off offset:2560
	v_add_co_u32_e32 v12, vcc, s5, v10
	s_mov_b32 s5, 0x37864000
	s_nop 0
	v_addc_co_u32_e32 v13, vcc, 0, v11, vcc
	v_add_co_u32_e32 v58, vcc, s5, v10
	s_mov_b32 s5, 0x20619000
	s_waitcnt vmcnt(16)
	v_pk_add_f32 v[38:39], v[38:39], v[54:55]
	v_addc_co_u32_e32 v59, vcc, 0, v11, vcc
	v_pk_mul_f32 v[54:55], v[38:39], v[38:39]
	v_add_co_u32_e32 v10, vcc, s5, v56
	v_add_f32_e32 v54, v54, v55
	v_mov_b32_e32 v55, v54
	v_addc_co_u32_e32 v11, vcc, 0, v57, vcc
	s_mov_b32 s5, 0x2061c000
	v_add_co_u32_e32 v56, vcc, s5, v56
	s_waitcnt lgkmcnt(0)
	s_nop 1
	v_permlane32_swap_b32_e32 v55, v54
	v_add_f32_e32 v54, v54, v55
	v_mov_b32_e32 v55, v54
	v_addc_co_u32_e32 v57, vcc, 0, v57, vcc
	global_load_dwordx2 v[14:15], v[12:13], off
	global_load_dwordx2 v[16:17], v[58:59], off
	s_waitcnt lgkmcnt(0)
	s_nop 1
	v_permlane16_swap_b32_e32 v55, v54
	v_add_f32_e32 v54, v54, v55
	s_waitcnt vmcnt(15)
	v_pk_add_f32 v[34:35], v[34:35], v[36:37]
	global_load_dword v47, v[10:11], off offset:512
	s_nop 0
	global_load_dwordx2 v[10:11], v[12:13], off offset:2048
	s_nop 0
	global_load_dwordx2 v[12:13], v[58:59], off offset:2048
	v_pk_mul_f32 v[36:37], v[34:35], v[34:35]
	global_load_dword v46, v[56:57], off offset:2560
	s_waitcnt lgkmcnt(0)
	s_nop 1
	v_add_f32_dpp v54, v54, v54 row_ror:8 row_mask:0xf bank_mask:0xf
	v_add_f32_e32 v36, v36, v37
	v_mov_b32_e32 v37, v36
	s_mov_b32 s5, 0x30601000
	s_add_i32 s4, s4, 8
	s_waitcnt lgkmcnt(0)
	s_nop 1
	v_add_f32_dpp v54, v54, v54 row_ror:4 row_mask:0xf bank_mask:0xf
	s_waitcnt lgkmcnt(0)
	s_nop 1
	v_permlane32_swap_b32_e32 v37, v36
	v_add_f32_e32 v36, v36, v37
	v_mov_b32_e32 v37, v36
	v_lshl_add_u64 v[2:3], v[2:3], 0, s[8:9]
	v_lshl_add_u64 v[6:7], v[6:7], 0, s[8:9]
	s_waitcnt lgkmcnt(0)
	s_nop 1
	v_add_f32_dpp v54, v54, v54 quad_perm:[2,3,0,1] row_mask:0xf bank_mask:0xf
	s_waitcnt lgkmcnt(0)
	s_nop 1
	v_permlane16_swap_b32_e32 v37, v36
	v_add_f32_e32 v36, v36, v37
	s_cmp_gt_u32 s4, 23
	s_waitcnt lgkmcnt(0)
	s_nop 1
	v_add_f32_dpp v54, v54, v54 quad_perm:[1,0,3,2] row_mask:0xf bank_mask:0xf
	v_fmamk_f32 v54, v54, 0x3c000000, v212
	v_cmp_gt_f32_e32 vcc, s1, v54
	v_mul_f32_e32 v55, 0x4b800000, v54
	s_waitcnt lgkmcnt(0)
	s_nop 1
	v_add_f32_dpp v36, v36, v36 row_ror:8 row_mask:0xf bank_mask:0xf
	v_cndmask_b32_e32 v54, v54, v55, vcc
	v_rsq_f32_e32 v54, v54
	s_waitcnt vmcnt(16)
	v_pk_add_f32 v[30:31], v[30:31], v[32:33]
	v_mul_f32_e32 v55, 0x45800000, v54
	v_cndmask_b32_e32 v54, v54, v55, vcc
	v_lshlrev_b32_e32 v55, 16, v53
	v_mul_f32_e32 v56, 0xbfb8aa3b, v55
	v_exp_f32_e32 v56, v56
	v_and_b32_e32 v53, 0xffff0000, v53
	v_mul_f32_e32 v38, v38, v54
	v_mul_f32_e32 v39, v39, v54
	v_add_f32_e32 v56, 1.0, v56
	v_div_scale_f32 v57, s[6:7], v56, v56, v55
	v_rcp_f32_e32 v58, v57
	v_mul_f32_e32 v54, 0xbfb8aa3b, v53
	v_exp_f32_e32 v54, v54
	v_mul_f32_e32 v38, v0, v38
	v_fma_f32 v59, -v57, v58, 1.0
	v_fmac_f32_e32 v58, v59, v58
	v_div_scale_f32 v59, vcc, v55, v56, v55
	v_mul_f32_e32 v60, v59, v58
	v_fma_f32 v61, -v57, v60, v59
	v_fmac_f32_e32 v60, v61, v58
	v_fma_f32 v57, -v57, v60, v59
	v_div_fmas_f32 v57, v57, v58, v60
	v_div_fixup_f32 v55, v57, v56, v55
	v_add_f32_e32 v54, 1.0, v54
	v_mul_f32_e32 v38, v55, v38
	v_div_scale_f32 v55, s[6:7], v54, v54, v53
	v_rcp_f32_e32 v56, v55
	s_waitcnt lgkmcnt(0)
; __device__ __forceinline__ unsigned cvt_pk_bf16(float lo, float hi) { unsigned r; asm("v_cvt_pk_bf16_f32 %0, %1, %2" : "=v"(r) : "v"(lo), "v"(hi)); return r; }
; __device__ __forceinline__ float bf_lo(unsigned w) { return __uint_as_float(w << 16); }
; __device__ __forceinline__ float bf_hi(unsigned w) { return __uint_as_float(w & 0xffff0000u); }
; __device__ __forceinline__ float wave_sum(float v) {
; #pragma unroll
;     for (int o = 32; o >= 1; o >>= 1) v += __shfl_xor(v, o);
;     return v;
; __device__ void gla_pass2(const Params& p, int l, const bf16_t* proj, bf16_t* ycat, LAS unsigned char* lds) {
;     ...
;         for (int j0 = 0; j0 < 32; j0 += 8) {
;             f32x2 of[8], ob[8]; unsigned rw[8];
; #pragma unroll
;             for (int j = 0; j < 8; ++j) { const int t = seg * SEGLEN + wv * 32 + j0 + j; const size_t oo = (size_t)t * 512 + h * 128 + lane * 2;
;                 of[j] = *(const f32x2*)(OF + oo); ob[j] = *(const f32x2*)(OB + oo); rw[j] = *(const unsigned*)(proj + (size_t)t * NP + GR + h * 128 + lane * 2); }
; #pragma unroll
;             for (int j = 0; j < 8; ++j) { const int t = seg * SEGLEN + wv * 32 + j0 + j;
;                 const float o0 = of[j][0] + ob[j][0], o1 = of[j][1] + ob[j][1];
;                 const float ss = wave_sum(o0 * o0 + o1 * o1);
;                 const float rs = rsqrtf(ss * (1.0f / 128.0f) + 1e-6f);
;                 const float r0 = bf_lo(rw[j]), r1 = bf_hi(rw[j]);
;                 const float y0 = o0 * rs * gg[0] * (r0 / (1.0f + __expf(-r0))), y1 = o1 * rs * gg[1] * (r1 / (1.0f + __expf(-r1)));
;                 *(unsigned*)(ycat + (size_t)2 * SEQ * 512 + (size_t)t * 512 + h * 128 + lane * 2) = cvt_pk_bf16(y0, y1); } }
	s_nop 1
	v_add_f32_dpp v36, v36, v36 row_ror:4 row_mask:0xf bank_mask:0xf
	v_mul_f32_e32 v39, v1, v39
	v_fma_f32 v57, -v55, v56, 1.0
	v_fmac_f32_e32 v56, v57, v56
	v_div_scale_f32 v57, vcc, v53, v54, v53
	v_mul_f32_e32 v58, v57, v56
	v_fma_f32 v59, -v55, v58, v57
	v_fmac_f32_e32 v58, v59, v56
	v_fma_f32 v55, -v55, v58, v57
	v_div_fmas_f32 v55, v55, v56, v58
	s_waitcnt lgkmcnt(0)
	s_nop 1
	v_add_f32_dpp v36, v36, v36 quad_perm:[2,3,0,1] row_mask:0xf bank_mask:0xf
	v_div_fixup_f32 v53, v55, v54, v53
	v_mul_f32_e32 v39, v53, v39
	v_cvt_pk_bf16_f32 v53, v38, v39
	v_lshl_add_u64 v[38:39], s[86:87], 0, v[8:9]
	v_add_co_u32_e32 v54, vcc, s5, v38
	s_mov_b32 s5, 0x30602000
	s_nop 0
	v_addc_co_u32_e32 v55, vcc, 0, v39, vcc
	v_add_co_u32_e32 v38, vcc, s5, v38
	s_waitcnt lgkmcnt(0)
	s_nop 1
	v_add_f32_dpp v36, v36, v36 quad_perm:[1,0,3,2] row_mask:0xf bank_mask:0xf
	v_addc_co_u32_e32 v39, vcc, 0, v39, vcc
	v_fmamk_f32 v36, v36, 0x3c000000, v212
	v_pk_mul_f32 v[32:33], v[30:31], v[30:31]
	v_cmp_gt_f32_e32 vcc, s1, v36
	v_mul_f32_e32 v37, 0x4b800000, v36
	v_add_f32_e32 v32, v32, v33
	v_cndmask_b32_e32 v36, v36, v37, vcc
	v_mov_b32_e32 v33, v32
	v_rsq_f32_e32 v36, v36
	global_store_dword v[38:39], v53, off offset:-4096
	s_waitcnt vmcnt(14)
	v_pk_add_f32 v[26:27], v[26:27], v[28:29]
	s_waitcnt vmcnt(11)
	v_pk_add_f32 v[22:23], v[22:23], v[24:25]
	v_mul_f32_e32 v37, 0x45800000, v36
	s_waitcnt lgkmcnt(0)
	s_nop 1
	v_permlane32_swap_b32_e32 v33, v32
	v_add_f32_e32 v32, v32, v33
	v_cndmask_b32_e32 v36, v36, v37, vcc
	v_lshlrev_b32_e32 v37, 16, v52
	v_mov_b32_e32 v33, v32
	v_mul_f32_e32 v53, 0xbfb8aa3b, v37
	v_exp_f32_e32 v53, v53
	v_and_b32_e32 v52, 0xffff0000, v52
	v_mul_f32_e32 v34, v34, v36
	s_waitcnt lgkmcnt(0)
	s_nop 1
	v_permlane16_swap_b32_e32 v33, v32
	v_add_f32_e32 v32, v32, v33
	v_add_f32_e32 v53, 1.0, v53
	v_div_scale_f32 v56, s[6:7], v53, v53, v37
	v_rcp_f32_e32 v57, v56
	v_mul_f32_e32 v35, v35, v36
	s_waitcnt lgkmcnt(0)
	s_nop 1
	v_add_f32_dpp v32, v32, v32 row_ror:8 row_mask:0xf bank_mask:0xf
	v_fma_f32 v58, -v56, v57, 1.0
	v_fmac_f32_e32 v57, v58, v57
	v_div_scale_f32 v58, vcc, v37, v53, v37
	v_mul_f32_e32 v59, v58, v57
	v_mul_f32_e32 v36, 0xbfb8aa3b, v52
	v_fma_f32 v60, -v56, v59, v58
	v_exp_f32_e32 v36, v36
	v_fmac_f32_e32 v59, v60, v57
	v_fma_f32 v56, -v56, v59, v58
	s_waitcnt lgkmcnt(0)
	s_nop 1
	v_add_f32_dpp v32, v32, v32 row_ror:4 row_mask:0xf bank_mask:0xf
	v_div_fmas_f32 v56, v56, v57, v59
	v_mul_f32_e32 v34, v0, v34
	v_div_fixup_f32 v37, v56, v53, v37
	v_add_f32_e32 v36, 1.0, v36
	v_mul_f32_e32 v34, v37, v34
	v_div_scale_f32 v37, s[6:7], v36, v36, v52
	v_rcp_f32_e32 v53, v37
	s_waitcnt lgkmcnt(0)
	s_nop 1
	v_add_f32_dpp v32, v32, v32 quad_perm:[2,3,0,1] row_mask:0xf bank_mask:0xf
	v_pk_mul_f32 v[28:29], v[26:27], v[26:27]
	v_fma_f32 v56, -v37, v53, 1.0
	v_fmac_f32_e32 v53, v56, v53
	v_div_scale_f32 v56, vcc, v52, v36, v52
	v_mul_f32_e32 v57, v56, v53
	v_fma_f32 v58, -v37, v57, v56
	v_fmac_f32_e32 v57, v58, v53
	s_waitcnt lgkmcnt(0)
	s_nop 1
	v_add_f32_dpp v32, v32, v32 quad_perm:[1,0,3,2] row_mask:0xf bank_mask:0xf
	v_fma_f32 v37, -v37, v57, v56
	v_fmamk_f32 v32, v32, 0x3c000000, v212
	v_div_fmas_f32 v37, v37, v53, v57
	v_cmp_gt_f32_e32 vcc, s1, v32
	v_mul_f32_e32 v33, 0x4b800000, v32
	v_add_f32_e32 v28, v28, v29
	v_cndmask_b32_e32 v32, v32, v33, vcc
	v_mov_b32_e32 v29, v28
	v_rsq_f32_e32 v32, v32
	v_mul_f32_e32 v35, v1, v35
	v_div_fixup_f32 v36, v37, v36, v52
	v_mul_f32_e32 v35, v36, v35
	v_mul_f32_e32 v33, 0x45800000, v32
	s_waitcnt lgkmcnt(0)
	s_nop 1
	v_permlane32_swap_b32_e32 v29, v28
	v_add_f32_e32 v28, v28, v29
	v_cndmask_b32_e32 v32, v32, v33, vcc
	v_lshlrev_b32_e32 v33, 16, v51
	v_mov_b32_e32 v29, v28
	v_cvt_pk_bf16_f32 v34, v34, v35
	v_mul_f32_e32 v35, 0xbfb8aa3b, v33
	v_exp_f32_e32 v35, v35
	global_store_dword v[54:55], v34, off offset:1024
	s_waitcnt lgkmcnt(0)
	s_nop 1
	v_permlane16_swap_b32_e32 v29, v28
	v_add_f32_e32 v28, v28, v29
	v_add_f32_e32 v35, 1.0, v35
	v_div_scale_f32 v36, s[6:7], v35, v35, v33
	v_rcp_f32_e32 v37, v36
	s_waitcnt lgkmcnt(0)
	s_nop 1
	v_add_f32_dpp v28, v28, v28 row_ror:8 row_mask:0xf bank_mask:0xf
	v_and_b32_e32 v34, 0xffff0000, v51
	v_fma_f32 v51, -v36, v37, 1.0
	v_fmac_f32_e32 v37, v51, v37
	v_div_scale_f32 v51, vcc, v33, v35, v33
	v_mul_f32_e32 v30, v30, v32
	v_mul_f32_e32 v52, v51, v37
	v_mul_f32_e32 v31, v31, v32
	v_mul_f32_e32 v32, 0xbfb8aa3b, v34
	v_fma_f32 v53, -v36, v52, v51
	v_exp_f32_e32 v32, v32
	v_fmac_f32_e32 v52, v53, v37
	v_fma_f32 v36, -v36, v52, v51
	s_waitcnt lgkmcnt(0)
	s_nop 1
	v_add_f32_dpp v28, v28, v28 row_ror:4 row_mask:0xf bank_mask:0xf
	v_div_fmas_f32 v36, v36, v37, v52
	v_mul_f32_e32 v30, v0, v30
	v_div_fixup_f32 v33, v36, v35, v33
	v_add_f32_e32 v32, 1.0, v32
	v_mul_f32_e32 v30, v33, v30
	v_div_scale_f32 v33, s[6:7], v32, v32, v34
	v_rcp_f32_e32 v35, v33
	s_waitcnt lgkmcnt(0)
	s_nop 1
	v_add_f32_dpp v28, v28, v28 quad_perm:[2,3,0,1] row_mask:0xf bank_mask:0xf
	v_pk_mul_f32 v[24:25], v[22:23], v[22:23]
	v_fma_f32 v36, -v33, v35, 1.0
	v_fmac_f32_e32 v35, v36, v35
	v_div_scale_f32 v36, vcc, v34, v32, v34
	v_mul_f32_e32 v37, v36, v35
	v_fma_f32 v51, -v33, v37, v36
	v_fmac_f32_e32 v37, v51, v35
	s_waitcnt lgkmcnt(0)
	s_nop 1
	v_add_f32_dpp v28, v28, v28 quad_perm:[1,0,3,2] row_mask:0xf bank_mask:0xf
	v_fma_f32 v33, -v33, v37, v36
	v_fmamk_f32 v28, v28, 0x3c000000, v212
	v_div_fmas_f32 v33, v33, v35, v37
	v_cmp_gt_f32_e32 vcc, s1, v28
	v_mul_f32_e32 v29, 0x4b800000, v28
	v_add_f32_e32 v24, v24, v25
	v_cndmask_b32_e32 v28, v28, v29, vcc
	v_mov_b32_e32 v25, v24
	v_rsq_f32_e32 v28, v28
	v_mul_f32_e32 v31, v1, v31
	v_div_fixup_f32 v32, v33, v32, v34
	v_mul_f32_e32 v31, v32, v31
	v_mul_f32_e32 v29, 0x45800000, v28
	s_waitcnt lgkmcnt(0)
; __device__ __forceinline__ unsigned cvt_pk_bf16(float lo, float hi) { unsigned r; asm("v_cvt_pk_bf16_f32 %0, %1, %2" : "=v"(r) : "v"(lo), "v"(hi)); return r; }
; __device__ __forceinline__ float bf_lo(unsigned w) { return __uint_as_float(w << 16); }
; __device__ __forceinline__ float bf_hi(unsigned w) { return __uint_as_float(w & 0xffff0000u); }
; __device__ __forceinline__ float wave_sum(float v) {
; #pragma unroll
;     for (int o = 32; o >= 1; o >>= 1) v += __shfl_xor(v, o);
;     return v;
; __device__ void gla_pass2(const Params& p, int l, const bf16_t* proj, bf16_t* ycat, LAS unsigned char* lds) {
;     ...
;         for (int j0 = 0; j0 < 32; j0 += 8) {
;             f32x2 of[8], ob[8]; unsigned rw[8];
; #pragma unroll
;             for (int j = 0; j < 8; ++j) { const int t = seg * SEGLEN + wv * 32 + j0 + j; const size_t oo = (size_t)t * 512 + h * 128 + lane * 2;
;                 of[j] = *(const f32x2*)(OF + oo); ob[j] = *(const f32x2*)(OB + oo); rw[j] = *(const unsigned*)(proj + (size_t)t * NP + GR + h * 128 + lane * 2); }
; #pragma unroll
;             for (int j = 0; j < 8; ++j) { const int t = seg * SEGLEN + wv * 32 + j0 + j;
;                 const float o0 = of[j][0] + ob[j][0], o1 = of[j][1] + ob[j][1];
;                 const float ss = wave_sum(o0 * o0 + o1 * o1);
;                 const float rs = rsqrtf(ss * (1.0f / 128.0f) + 1e-6f);
;                 const float r0 = bf_lo(rw[j]), r1 = bf_hi(rw[j]);
;                 const float y0 = o0 * rs * gg[0] * (r0 / (1.0f + __expf(-r0))), y1 = o1 * rs * gg[1] * (r1 / (1.0f + __expf(-r1)));
;                 *(unsigned*)(ycat + (size_t)2 * SEQ * 512 + (size_t)t * 512 + h * 128 + lane * 2) = cvt_pk_bf16(y0, y1); } }
	s_nop 1
	v_permlane32_swap_b32_e32 v25, v24
	v_add_f32_e32 v24, v24, v25
	v_cndmask_b32_e32 v28, v28, v29, vcc
	v_lshlrev_b32_e32 v29, 16, v50
	v_mov_b32_e32 v25, v24
	v_cvt_pk_bf16_f32 v30, v30, v31
	v_mul_f32_e32 v31, 0xbfb8aa3b, v29
	v_exp_f32_e32 v31, v31
	global_store_dword v[54:55], v30, off offset:2048
	s_waitcnt lgkmcnt(0)
	s_nop 1
	v_permlane16_swap_b32_e32 v25, v24
	v_add_f32_e32 v24, v24, v25
	v_add_f32_e32 v31, 1.0, v31
	v_div_scale_f32 v32, s[6:7], v31, v31, v29
	v_rcp_f32_e32 v33, v32
	s_waitcnt lgkmcnt(0)
	s_nop 1
	v_add_f32_dpp v24, v24, v24 row_ror:8 row_mask:0xf bank_mask:0xf
	v_and_b32_e32 v30, 0xffff0000, v50
	v_fma_f32 v34, -v32, v33, 1.0
	v_fmac_f32_e32 v33, v34, v33
	v_div_scale_f32 v34, vcc, v29, v31, v29
	v_mul_f32_e32 v26, v26, v28
	v_mul_f32_e32 v35, v34, v33
	v_mul_f32_e32 v27, v27, v28
	v_mul_f32_e32 v28, 0xbfb8aa3b, v30
	v_fma_f32 v36, -v32, v35, v34
	v_exp_f32_e32 v28, v28
	v_fmac_f32_e32 v35, v36, v33
	v_fma_f32 v32, -v32, v35, v34
	s_waitcnt lgkmcnt(0)
	s_nop 1
	v_add_f32_dpp v24, v24, v24 row_ror:4 row_mask:0xf bank_mask:0xf
	v_div_fmas_f32 v32, v32, v33, v35
	v_mul_f32_e32 v26, v0, v26
	v_div_fixup_f32 v29, v32, v31, v29
	v_add_f32_e32 v28, 1.0, v28
	v_mul_f32_e32 v26, v29, v26
	v_div_scale_f32 v29, s[6:7], v28, v28, v30
	v_rcp_f32_e32 v31, v29
	s_waitcnt lgkmcnt(0)
	s_nop 1
	v_add_f32_dpp v24, v24, v24 quad_perm:[2,3,0,1] row_mask:0xf bank_mask:0xf
	s_waitcnt vmcnt(10)
	v_pk_add_f32 v[18:19], v[18:19], v[20:21]
	v_fma_f32 v32, -v29, v31, 1.0
	v_fmac_f32_e32 v31, v32, v31
	v_div_scale_f32 v32, vcc, v30, v28, v30
	v_mul_f32_e32 v33, v32, v31
	v_fma_f32 v34, -v29, v33, v32
	v_fmac_f32_e32 v33, v34, v31
	s_waitcnt lgkmcnt(0)
	s_nop 1
	v_add_f32_dpp v24, v24, v24 quad_perm:[1,0,3,2] row_mask:0xf bank_mask:0xf
	v_fma_f32 v29, -v29, v33, v32
	v_fmamk_f32 v24, v24, 0x3c000000, v212
	v_pk_mul_f32 v[20:21], v[18:19], v[18:19]
	v_div_fmas_f32 v29, v29, v31, v33
	v_cmp_gt_f32_e32 vcc, s1, v24
	v_mul_f32_e32 v25, 0x4b800000, v24
	v_add_f32_e32 v20, v20, v21
	v_cndmask_b32_e32 v24, v24, v25, vcc
	v_mov_b32_e32 v21, v20
	v_rsq_f32_e32 v24, v24
	v_mul_f32_e32 v27, v1, v27
	v_div_fixup_f32 v28, v29, v28, v30
	v_mul_f32_e32 v27, v28, v27
	v_mul_f32_e32 v25, 0x45800000, v24
	s_waitcnt lgkmcnt(0)
	s_nop 1
	v_permlane32_swap_b32_e32 v21, v20
	v_add_f32_e32 v20, v20, v21
	v_cndmask_b32_e32 v24, v24, v25, vcc
	v_lshlrev_b32_e32 v25, 16, v49
	v_mov_b32_e32 v21, v20
	v_cvt_pk_bf16_f32 v26, v26, v27
	v_mul_f32_e32 v27, 0xbfb8aa3b, v25
	v_exp_f32_e32 v27, v27
	global_store_dword v[54:55], v26, off offset:3072
	s_waitcnt lgkmcnt(0)
	s_nop 1
	v_permlane16_swap_b32_e32 v21, v20
	v_add_f32_e32 v20, v20, v21
	v_add_f32_e32 v27, 1.0, v27
	v_div_scale_f32 v28, s[6:7], v27, v27, v25
	v_rcp_f32_e32 v29, v28
	s_waitcnt lgkmcnt(0)
	s_nop 1
	v_add_f32_dpp v20, v20, v20 row_ror:8 row_mask:0xf bank_mask:0xf
	v_and_b32_e32 v26, 0xffff0000, v49
	v_fma_f32 v30, -v28, v29, 1.0
	v_fmac_f32_e32 v29, v30, v29
	v_div_scale_f32 v30, vcc, v25, v27, v25
	v_mul_f32_e32 v22, v22, v24
	v_mul_f32_e32 v31, v30, v29
	v_mul_f32_e32 v23, v23, v24
	v_mul_f32_e32 v24, 0xbfb8aa3b, v26
	v_fma_f32 v32, -v28, v31, v30
	v_exp_f32_e32 v24, v24
	v_fmac_f32_e32 v31, v32, v29
	v_fma_f32 v28, -v28, v31, v30
	s_waitcnt lgkmcnt(0)
	s_nop 1
	v_add_f32_dpp v20, v20, v20 row_ror:4 row_mask:0xf bank_mask:0xf
	v_div_fmas_f32 v28, v28, v29, v31
	v_mul_f32_e32 v22, v0, v22
	v_div_fixup_f32 v25, v28, v27, v25
	v_add_f32_e32 v24, 1.0, v24
	v_mul_f32_e32 v22, v25, v22
	v_div_scale_f32 v25, s[6:7], v24, v24, v26
	v_rcp_f32_e32 v27, v25
	s_waitcnt lgkmcnt(0)
	s_nop 1
	v_add_f32_dpp v20, v20, v20 quad_perm:[2,3,0,1] row_mask:0xf bank_mask:0xf
	s_waitcnt vmcnt(8)
	v_pk_add_f32 v[14:15], v[14:15], v[16:17]
	v_fma_f32 v28, -v25, v27, 1.0
	v_fmac_f32_e32 v27, v28, v27
	v_div_scale_f32 v28, vcc, v26, v24, v26
	v_mul_f32_e32 v29, v28, v27
	v_fma_f32 v30, -v25, v29, v28
	v_fmac_f32_e32 v29, v30, v27
	s_waitcnt lgkmcnt(0)
	s_nop 1
	v_add_f32_dpp v20, v20, v20 quad_perm:[1,0,3,2] row_mask:0xf bank_mask:0xf
	v_fma_f32 v25, -v25, v29, v28
	v_fmamk_f32 v20, v20, 0x3c000000, v212
	v_pk_mul_f32 v[16:17], v[14:15], v[14:15]
	v_div_fmas_f32 v25, v25, v27, v29
	v_cmp_gt_f32_e32 vcc, s1, v20
	v_mul_f32_e32 v21, 0x4b800000, v20
	v_add_f32_e32 v16, v16, v17
	v_cndmask_b32_e32 v20, v20, v21, vcc
	v_mov_b32_e32 v17, v16
	v_rsq_f32_e32 v20, v20
	v_mul_f32_e32 v23, v1, v23
	v_div_fixup_f32 v24, v25, v24, v26
	v_mul_f32_e32 v23, v24, v23
	v_mul_f32_e32 v21, 0x45800000, v20
	s_waitcnt lgkmcnt(0)
	s_nop 1
	v_permlane32_swap_b32_e32 v17, v16
	v_add_f32_e32 v16, v16, v17
	v_cndmask_b32_e32 v20, v20, v21, vcc
	v_lshlrev_b32_e32 v21, 16, v48
	v_mov_b32_e32 v17, v16
	v_cvt_pk_bf16_f32 v22, v22, v23
	v_mul_f32_e32 v23, 0xbfb8aa3b, v21
	v_exp_f32_e32 v23, v23
	global_store_dword v[38:39], v22, off
	s_waitcnt lgkmcnt(0)
	s_nop 1
	v_permlane16_swap_b32_e32 v17, v16
	v_add_f32_e32 v16, v16, v17
	v_add_f32_e32 v23, 1.0, v23
	v_div_scale_f32 v24, s[6:7], v23, v23, v21
	v_rcp_f32_e32 v25, v24
	s_waitcnt lgkmcnt(0)
	s_nop 1
	v_add_f32_dpp v16, v16, v16 row_ror:8 row_mask:0xf bank_mask:0xf
	v_and_b32_e32 v22, 0xffff0000, v48
	v_fma_f32 v26, -v24, v25, 1.0
	v_fmac_f32_e32 v25, v26, v25
	v_div_scale_f32 v26, vcc, v21, v23, v21
	v_mul_f32_e32 v18, v18, v20
	v_mul_f32_e32 v27, v26, v25
	v_mul_f32_e32 v19, v19, v20
	v_mul_f32_e32 v20, 0xbfb8aa3b, v22
	v_fma_f32 v28, -v24, v27, v26
	v_exp_f32_e32 v20, v20
	v_fmac_f32_e32 v27, v28, v25
	v_fma_f32 v24, -v24, v27, v26
	s_waitcnt lgkmcnt(0)
; __device__ __forceinline__ unsigned cvt_pk_bf16(float lo, float hi) { unsigned r; asm("v_cvt_pk_bf16_f32 %0, %1, %2" : "=v"(r) : "v"(lo), "v"(hi)); return r; }
; __device__ __forceinline__ float bf_lo(unsigned w) { return __uint_as_float(w << 16); }
; __device__ __forceinline__ float bf_hi(unsigned w) { return __uint_as_float(w & 0xffff0000u); }
; __device__ __forceinline__ float wave_sum(float v) {
; #pragma unroll
;     for (int o = 32; o >= 1; o >>= 1) v += __shfl_xor(v, o);
;     return v;
; __device__ void gla_pass2(const Params& p, int l, const bf16_t* proj, bf16_t* ycat, LAS unsigned char* lds) {
;     ...
;         for (int j0 = 0; j0 < 32; j0 += 8) {
;             f32x2 of[8], ob[8]; unsigned rw[8];
; #pragma unroll
;             for (int j = 0; j < 8; ++j) { const int t = seg * SEGLEN + wv * 32 + j0 + j; const size_t oo = (size_t)t * 512 + h * 128 + lane * 2;
;                 of[j] = *(const f32x2*)(OF + oo); ob[j] = *(const f32x2*)(OB + oo); rw[j] = *(const unsigned*)(proj + (size_t)t * NP + GR + h * 128 + lane * 2); }
; #pragma unroll
;             for (int j = 0; j < 8; ++j) { const int t = seg * SEGLEN + wv * 32 + j0 + j;
;                 const float o0 = of[j][0] + ob[j][0], o1 = of[j][1] + ob[j][1];
;                 const float ss = wave_sum(o0 * o0 + o1 * o1);
;                 const float rs = rsqrtf(ss * (1.0f / 128.0f) + 1e-6f);
;                 const float r0 = bf_lo(rw[j]), r1 = bf_hi(rw[j]);
;                 const float y0 = o0 * rs * gg[0] * (r0 / (1.0f + __expf(-r0))), y1 = o1 * rs * gg[1] * (r1 / (1.0f + __expf(-r1)));
;                 *(unsigned*)(ycat + (size_t)2 * SEQ * 512 + (size_t)t * 512 + h * 128 + lane * 2) = cvt_pk_bf16(y0, y1); } }
;         __syncthreads();
;     }
	s_nop 1
	v_add_f32_dpp v16, v16, v16 row_ror:4 row_mask:0xf bank_mask:0xf
	v_div_fmas_f32 v24, v24, v25, v27
	v_mul_f32_e32 v18, v0, v18
	v_div_fixup_f32 v21, v24, v23, v21
	v_add_f32_e32 v20, 1.0, v20
	v_mul_f32_e32 v18, v21, v18
	v_div_scale_f32 v21, s[6:7], v20, v20, v22
	v_rcp_f32_e32 v23, v21
	s_waitcnt lgkmcnt(0)
	s_nop 1
	v_add_f32_dpp v16, v16, v16 quad_perm:[2,3,0,1] row_mask:0xf bank_mask:0xf
	s_waitcnt vmcnt(6)
	v_pk_add_f32 v[10:11], v[10:11], v[12:13]
	v_fma_f32 v24, -v21, v23, 1.0
	v_fmac_f32_e32 v23, v24, v23
	v_div_scale_f32 v24, vcc, v22, v20, v22
	v_mul_f32_e32 v25, v24, v23
	v_fma_f32 v26, -v21, v25, v24
	v_fmac_f32_e32 v25, v26, v23
	s_waitcnt lgkmcnt(0)
	s_nop 1
	v_add_f32_dpp v16, v16, v16 quad_perm:[1,0,3,2] row_mask:0xf bank_mask:0xf
	v_fma_f32 v21, -v21, v25, v24
	v_fmamk_f32 v16, v16, 0x3c000000, v212
	v_pk_mul_f32 v[12:13], v[10:11], v[10:11]
	v_div_fmas_f32 v21, v21, v23, v25
	v_cmp_gt_f32_e32 vcc, s1, v16
	v_mul_f32_e32 v17, 0x4b800000, v16
	v_add_f32_e32 v12, v12, v13
	v_cndmask_b32_e32 v16, v16, v17, vcc
	v_mov_b32_e32 v13, v12
	v_rsq_f32_e32 v16, v16
	v_mul_f32_e32 v19, v1, v19
	v_div_fixup_f32 v20, v21, v20, v22
	v_mul_f32_e32 v19, v20, v19
	v_mul_f32_e32 v17, 0x45800000, v16
	s_waitcnt lgkmcnt(0)
	s_nop 1
	v_permlane32_swap_b32_e32 v13, v12
	v_add_f32_e32 v12, v12, v13
	v_cndmask_b32_e32 v16, v16, v17, vcc
	v_lshlrev_b32_e32 v17, 16, v47
	v_mov_b32_e32 v13, v12
	v_cvt_pk_bf16_f32 v18, v18, v19
	v_mul_f32_e32 v19, 0xbfb8aa3b, v17
	v_exp_f32_e32 v19, v19
	global_store_dword v[38:39], v18, off offset:1024
	s_waitcnt lgkmcnt(0)
	s_nop 1
	v_permlane16_swap_b32_e32 v13, v12
	v_add_f32_e32 v12, v12, v13
	v_add_f32_e32 v19, 1.0, v19
	v_div_scale_f32 v20, s[6:7], v19, v19, v17
	v_rcp_f32_e32 v21, v20
	s_waitcnt lgkmcnt(0)
	s_nop 1
	v_add_f32_dpp v12, v12, v12 row_ror:8 row_mask:0xf bank_mask:0xf
	v_and_b32_e32 v18, 0xffff0000, v47
	v_fma_f32 v22, -v20, v21, 1.0
	v_fmac_f32_e32 v21, v22, v21
	v_div_scale_f32 v22, vcc, v17, v19, v17
	v_mul_f32_e32 v14, v14, v16
	v_mul_f32_e32 v23, v22, v21
	v_mul_f32_e32 v15, v15, v16
	v_mul_f32_e32 v16, 0xbfb8aa3b, v18
	v_fma_f32 v24, -v20, v23, v22
	v_exp_f32_e32 v16, v16
	v_fmac_f32_e32 v23, v24, v21
	v_fma_f32 v20, -v20, v23, v22
	s_waitcnt lgkmcnt(0)
	s_nop 1
	v_add_f32_dpp v12, v12, v12 row_ror:4 row_mask:0xf bank_mask:0xf
	v_div_fmas_f32 v20, v20, v21, v23
	v_mul_f32_e32 v14, v0, v14
	v_div_fixup_f32 v17, v20, v19, v17
	v_add_f32_e32 v16, 1.0, v16
	v_mul_f32_e32 v14, v17, v14
	v_div_scale_f32 v17, s[6:7], v16, v16, v18
	v_rcp_f32_e32 v19, v17
	s_waitcnt lgkmcnt(0)
	s_nop 1
	v_add_f32_dpp v12, v12, v12 quad_perm:[2,3,0,1] row_mask:0xf bank_mask:0xf
	v_mul_f32_e32 v15, v1, v15
	v_fma_f32 v20, -v17, v19, 1.0
	v_fmac_f32_e32 v19, v20, v19
	v_div_scale_f32 v20, vcc, v18, v16, v18
	v_mul_f32_e32 v21, v20, v19
	v_fma_f32 v22, -v17, v21, v20
	v_fmac_f32_e32 v21, v22, v19
	s_waitcnt lgkmcnt(0)
	s_nop 1
	v_add_f32_dpp v12, v12, v12 quad_perm:[1,0,3,2] row_mask:0xf bank_mask:0xf
	v_fma_f32 v17, -v17, v21, v20
	v_fmamk_f32 v12, v12, 0x3c000000, v212
	v_div_fmas_f32 v17, v17, v19, v21
	v_cmp_gt_f32_e32 vcc, s1, v12
	v_mul_f32_e32 v13, 0x4b800000, v12
	v_div_fixup_f32 v16, v17, v16, v18
	v_cndmask_b32_e32 v12, v12, v13, vcc
	v_rsq_f32_e32 v12, v12
	v_mul_f32_e32 v15, v16, v15
	v_cvt_pk_bf16_f32 v14, v14, v15
	global_store_dword v[38:39], v14, off offset:2048
	v_mul_f32_e32 v13, 0x45800000, v12
	v_cndmask_b32_e32 v12, v12, v13, vcc
	s_waitcnt vmcnt(7)
	v_lshlrev_b32_e32 v13, 16, v46
	v_mul_f32_e32 v15, 0xbfb8aa3b, v13
	v_exp_f32_e32 v15, v15
	v_and_b32_e32 v14, 0xffff0000, v46
	v_mul_f32_e32 v10, v10, v12
	v_mul_f32_e32 v11, v11, v12
	v_add_f32_e32 v15, 1.0, v15
	v_div_scale_f32 v16, s[6:7], v15, v15, v13
	v_rcp_f32_e32 v17, v16
	v_mul_f32_e32 v12, 0xbfb8aa3b, v14
	v_exp_f32_e32 v12, v12
	v_mul_f32_e32 v10, v0, v10
	v_fma_f32 v18, -v16, v17, 1.0
	v_fmac_f32_e32 v17, v18, v17
	v_div_scale_f32 v18, vcc, v13, v15, v13
	v_mul_f32_e32 v19, v18, v17
	v_fma_f32 v20, -v16, v19, v18
	v_fmac_f32_e32 v19, v20, v17
	v_fma_f32 v16, -v16, v19, v18
	v_div_fmas_f32 v16, v16, v17, v19
	v_div_fixup_f32 v13, v16, v15, v13
	v_add_f32_e32 v12, 1.0, v12
	v_mul_f32_e32 v10, v13, v10
	v_div_scale_f32 v13, s[6:7], v12, v12, v14
	v_rcp_f32_e32 v15, v13
	s_mov_b64 s[6:7], 0x1c000
	v_lshl_add_u64 v[4:5], v[4:5], 0, s[6:7]
	s_mov_b64 s[6:7], 0x2000
	v_fma_f32 v16, -v13, v15, 1.0
	v_fmac_f32_e32 v15, v16, v15
	v_div_scale_f32 v16, vcc, v14, v12, v14
	v_mul_f32_e32 v17, v16, v15
	v_fma_f32 v18, -v13, v17, v16
	v_fmac_f32_e32 v17, v18, v15
	v_fma_f32 v13, -v13, v17, v16
	v_div_fmas_f32 v13, v13, v15, v17
	v_mul_f32_e32 v11, v1, v11
	v_div_fixup_f32 v12, v13, v12, v14
	v_lshl_add_u64 v[8:9], v[8:9], 0, s[6:7]
	v_mul_f32_e32 v11, v12, v11
	v_cvt_pk_bf16_f32 v10, v10, v11
	global_store_dword v[38:39], v10, off offset:3072
	s_cbranch_scc0 .LBB0_443
	v_readlane_b32 s58, v255, 59
	s_add_i32 s58, s58, s59
	s_add_i32 s10, s10, s59
	s_cmpk_gt_i32 s58, 0xff
	s_barrier
	s_cbranch_scc0 .LBB0_432
	v_readlane_b32 s56, v255, 51
	v_readlane_b32 s76, v255, 43
	v_readlane_b32 s72, v255, 35
	v_readlane_b32 s66, v255, 21
	v_readlane_b32 s28, v255, 23
	v_readlane_b32 s57, v255, 52
	v_readlane_b32 s77, v255, 44
	v_readlane_b32 s78, v255, 45
	v_readlane_b32 s79, v255, 46
	v_readlane_b32 s80, v255, 47
	v_readlane_b32 s81, v255, 48
	v_readlane_b32 s82, v255, 49
	v_readlane_b32 s83, v255, 50
	v_readlane_b32 s58, v255, 57
	v_readlane_b32 s61, v255, 42
	v_readlane_b32 s73, v255, 36
	v_readlane_b32 s67, v255, 22
	v_readlane_b32 s29, v255, 24
	v_readlane_b32 s30, v255, 25
	v_readlane_b32 s64, v255, 41
	v_readlane_b32 s33, v255, 27
	v_readlane_b32 s68, v255, 28
	v_readlane_b32 s62, v255, 40
	v_readlane_b32 s69, v255, 29
	v_readlane_b32 s84, v255, 30
	v_readlane_b32 s85, v255, 39
	v_readlane_b32 s34, v255, 31
	v_readlane_b32 s35, v255, 32
	v_readlane_b32 s36, v255, 33
	v_readlane_b32 s37, v255, 34
	v_readlane_b32 s26, v255, 53
	v_readlane_b32 s31, v255, 26
	v_readlane_b32 s27, v255, 54
